# GEMM K loops: LDS-DMA loads use scalar base + 32-bit lane offset instead of 64-bit VGPR addresses (16 v_lshl_add_u64 per iteration removed)
# speedup vs baseline: 1.0046x; 1.0046x over previous
.LBB0_100:
	s_add_u32 s21, s48, 0xfff00080
	s_addc_u32 s28, s49, -1
	s_add_i32 s60, 0, 0x10000
	v_add_u32_e32 v124, s60, v175
	ds_read_b128 v[112:115], v124
	ds_read_b128 v[116:119], v124 offset:1024
	ds_read_b128 v[120:123], v124 offset:2048
	ds_read_b128 v[124:127], v124 offset:3072
	s_cmp_eq_u32 s20, 60
	s_cselect_b32 s51, s43, s28
	s_cselect_b32 s50, s24, s21
	s_cselect_b32 s29, s1, vcc_hi
	s_cselect_b32 s28, s25, vcc_lo
	s_add_i32 m0, s55, 0xc000
	ds_read_b128 v[128:131], v199
	ds_read_b128 v[132:135], v199 offset:1024
	ds_read_b128 v[162:165], v199 offset:2048
	ds_read_b128 v[166:169], v199 offset:3072
	ds_read_b128 v[170:173], v199 offset:4096
	ds_read_b128 v[200:203], v199 offset:5120
	ds_read_b128 v[204:207], v199 offset:6144
	ds_read_b128 v[208:211], v199 offset:7168
	global_load_lds_dwordx4 v158, s[48:49]
	s_add_i32 m0, s55, 0xe000
	s_nop 0
	global_load_lds_dwordx4 v160, s[48:49]
	s_waitcnt lgkmcnt(8)
	s_barrier
	s_waitcnt lgkmcnt(0)
	v_mfma_f32_16x16x32_bf16 v[148:151], v[112:115], v[128:131], v[148:151]
	v_mfma_f32_16x16x32_bf16 v[144:147], v[120:123], v[128:131], v[144:147]
	v_mfma_f32_16x16x32_bf16 v[108:111], v[112:115], v[162:165], v[108:111]
	v_mfma_f32_16x16x32_bf16 v[104:107], v[120:123], v[162:165], v[104:107]
	v_mfma_f32_16x16x32_bf16 v[92:95], v[112:115], v[170:173], v[92:95]
	v_mfma_f32_16x16x32_bf16 v[88:91], v[120:123], v[170:173], v[88:91]
	v_mfma_f32_16x16x32_bf16 v[76:79], v[112:115], v[204:207], v[76:79]
	v_mfma_f32_16x16x32_bf16 v[72:75], v[120:123], v[204:207], v[72:75]
	v_mfma_f32_16x16x32_bf16 v[148:151], v[116:119], v[132:135], v[148:151]
	v_mfma_f32_16x16x32_bf16 v[144:147], v[124:127], v[132:135], v[144:147]
	v_mfma_f32_16x16x32_bf16 v[108:111], v[116:119], v[166:169], v[108:111]
	v_mfma_f32_16x16x32_bf16 v[104:107], v[124:127], v[166:169], v[104:107]
	v_mfma_f32_16x16x32_bf16 v[92:95], v[116:119], v[200:203], v[92:95]
	v_mfma_f32_16x16x32_bf16 v[88:91], v[124:127], v[200:203], v[88:91]
	v_mfma_f32_16x16x32_bf16 v[76:79], v[116:119], v[208:211], v[76:79]
	v_mfma_f32_16x16x32_bf16 v[72:75], v[124:127], v[208:211], v[72:75]
	s_barrier
	s_add_i32 s21, 0, 0x14000
	v_add_u32_e32 v184, s21, v175
	s_add_i32 s60, s60, s54
	ds_read_b128 v[212:215], v184
	ds_read_b128 v[216:219], v184 offset:1024
	ds_read_b128 v[232:235], v184 offset:2048
	ds_read_b128 v[236:239], v184 offset:3072
	s_add_u32 s72, s28, s52
	s_addc_u32 s73, s29, s53
	s_mov_b32 m0, s60
	s_nop 0
	global_load_lds_dwordx4 v176, s[28:29]
	s_add_i32 m0, s60, 0x2000
	s_nop 0
	global_load_lds_dwordx4 v152, s[28:29]
	s_barrier
	s_waitcnt lgkmcnt(0)
	v_mfma_f32_16x16x32_bf16 v[140:143], v[212:215], v[128:131], v[140:143]
	v_mfma_f32_16x16x32_bf16 v[100:103], v[212:215], v[162:165], v[100:103]
	v_mfma_f32_16x16x32_bf16 v[96:99], v[232:235], v[162:165], v[96:99]
	v_mfma_f32_16x16x32_bf16 v[84:87], v[212:215], v[170:173], v[84:87]
	v_mfma_f32_16x16x32_bf16 v[80:83], v[232:235], v[170:173], v[80:83]
	v_mfma_f32_16x16x32_bf16 v[68:71], v[212:215], v[204:207], v[68:71]
	v_mfma_f32_16x16x32_bf16 v[64:67], v[232:235], v[204:207], v[64:67]
	v_mfma_f32_16x16x32_bf16 v[140:143], v[216:219], v[132:135], v[140:143]
	v_mfma_f32_16x16x32_bf16 v[128:131], v[232:235], v[128:131], v[136:139]
	v_mfma_f32_16x16x32_bf16 v[100:103], v[216:219], v[166:169], v[100:103]
	v_mfma_f32_16x16x32_bf16 v[96:99], v[236:239], v[166:169], v[96:99]
	v_mfma_f32_16x16x32_bf16 v[84:87], v[216:219], v[200:203], v[84:87]
	v_mfma_f32_16x16x32_bf16 v[80:83], v[236:239], v[200:203], v[80:83]
	v_mfma_f32_16x16x32_bf16 v[68:71], v[216:219], v[208:211], v[68:71]
	v_mfma_f32_16x16x32_bf16 v[64:67], v[236:239], v[208:211], v[64:67]
	v_mfma_f32_16x16x32_bf16 v[128:131], v[236:239], v[132:135], v[128:131]
	s_mov_b32 m0, s55
	s_add_u32 s94, s50, s52
	s_addc_u32 s95, s51, s53
	s_barrier
	ds_read_b128 v[132:135], v199 offset:16384
	ds_read_b128 v[136:139], v199 offset:17408
	ds_read_b128 v[162:165], v199 offset:18432
	ds_read_b128 v[166:169], v199 offset:19456
	ds_read_b128 v[170:173], v199 offset:20480
	ds_read_b128 v[200:203], v199 offset:21504
	ds_read_b128 v[204:207], v199 offset:22528
	ds_read_b128 v[208:211], v199 offset:23552
	global_load_lds_dwordx4 v156, s[50:51]
	s_mov_b32 m0, s56
	s_nop 0
	global_load_lds_dwordx4 v154, s[50:51]
	s_barrier
	s_waitcnt lgkmcnt(0)
	v_mfma_f32_16x16x32_bf16 v[60:63], v[112:115], v[132:135], v[60:63]
	v_mfma_f32_16x16x32_bf16 v[56:59], v[120:123], v[132:135], v[56:59]
	v_mfma_f32_16x16x32_bf16 v[44:47], v[112:115], v[162:165], v[44:47]
	v_mfma_f32_16x16x32_bf16 v[40:43], v[120:123], v[162:165], v[40:43]
	v_mfma_f32_16x16x32_bf16 v[28:31], v[112:115], v[170:173], v[28:31]
	v_mfma_f32_16x16x32_bf16 v[24:27], v[120:123], v[170:173], v[24:27]
	v_mfma_f32_16x16x32_bf16 v[12:15], v[112:115], v[204:207], v[12:15]
	v_mfma_f32_16x16x32_bf16 v[8:11], v[120:123], v[204:207], v[8:11]
	v_mfma_f32_16x16x32_bf16 v[60:63], v[116:119], v[136:139], v[60:63]
	v_mfma_f32_16x16x32_bf16 v[56:59], v[124:127], v[136:139], v[56:59]
	v_mfma_f32_16x16x32_bf16 v[44:47], v[116:119], v[166:169], v[44:47]
	v_mfma_f32_16x16x32_bf16 v[40:43], v[124:127], v[166:169], v[40:43]
	v_mfma_f32_16x16x32_bf16 v[28:31], v[116:119], v[200:203], v[28:31]
	v_mfma_f32_16x16x32_bf16 v[24:27], v[124:127], v[200:203], v[24:27]
	v_mfma_f32_16x16x32_bf16 v[12:15], v[116:119], v[208:211], v[12:15]
	v_mfma_f32_16x16x32_bf16 v[8:11], v[124:127], v[208:211], v[8:11]
	s_barrier
	s_add_u32 s60, s28, 0x100000
	s_addc_u32 s61, s29, 0
	s_add_i32 s21, s21, s54
	s_mov_b32 m0, s21
	s_nop 0
	global_load_lds_dwordx4 v176, s[60:61]
	s_add_i32 m0, s21, 0x2000
	s_nop 0
	global_load_lds_dwordx4 v152, s[60:61]
	s_waitcnt vmcnt(6)
	s_barrier
	v_mfma_f32_16x16x32_bf16 v[52:55], v[212:215], v[132:135], v[52:55]
	v_mfma_f32_16x16x32_bf16 v[48:51], v[232:235], v[132:135], v[48:51]
	v_mfma_f32_16x16x32_bf16 v[36:39], v[212:215], v[162:165], v[36:39]
	v_mfma_f32_16x16x32_bf16 v[32:35], v[232:235], v[162:165], v[32:35]
	v_mfma_f32_16x16x32_bf16 v[20:23], v[212:215], v[170:173], v[20:23]
	v_mfma_f32_16x16x32_bf16 v[16:19], v[232:235], v[170:173], v[16:19]
	v_mfma_f32_16x16x32_bf16 v[4:7], v[212:215], v[204:207], v[4:7]
	v_mfma_f32_16x16x32_bf16 v[0:3], v[232:235], v[204:207], v[0:3]
	v_mfma_f32_16x16x32_bf16 v[52:55], v[216:219], v[136:139], v[52:55]
	v_mfma_f32_16x16x32_bf16 v[48:51], v[236:239], v[136:139], v[48:51]
	v_mfma_f32_16x16x32_bf16 v[36:39], v[216:219], v[166:169], v[36:39]
	v_mfma_f32_16x16x32_bf16 v[32:35], v[236:239], v[166:169], v[32:35]
	v_mfma_f32_16x16x32_bf16 v[20:23], v[216:219], v[200:203], v[20:23]
	v_mfma_f32_16x16x32_bf16 v[16:19], v[236:239], v[200:203], v[16:19]
	v_mfma_f32_16x16x32_bf16 v[4:7], v[216:219], v[208:211], v[4:7]
	v_mfma_f32_16x16x32_bf16 v[0:3], v[236:239], v[208:211], v[0:3]
	s_add_i32 s21, 0, 0x18000
	v_add_u32_e32 v124, s21, v175
	s_barrier
	ds_read_b128 v[112:115], v124
	ds_read_b128 v[116:119], v124 offset:1024
	ds_read_b128 v[120:123], v124 offset:2048
	ds_read_b128 v[124:127], v124 offset:3072
	s_add_u32 s50, s50, 0x100000
	s_addc_u32 s51, s51, 0
	s_mov_b32 m0, s57
	ds_read_b128 v[132:135], v199 offset:32768
	ds_read_b128 v[136:139], v199 offset:33792
	ds_read_b128 v[162:165], v199 offset:34816
	ds_read_b128 v[166:169], v199 offset:35840
	ds_read_b128 v[170:173], v199 offset:36864
	ds_read_b128 v[200:203], v199 offset:37888
	ds_read_b128 v[204:207], v199 offset:38912
	ds_read_b128 v[208:211], v199 offset:39936
	global_load_lds_dwordx4 v156, s[50:51]
	s_mov_b32 m0, s58
	s_nop 0
	global_load_lds_dwordx4 v154, s[50:51]
	s_waitcnt lgkmcnt(8)
	s_barrier
	s_waitcnt lgkmcnt(0)
	v_mfma_f32_16x16x32_bf16 v[148:151], v[112:115], v[132:135], v[148:151]
	v_mfma_f32_16x16x32_bf16 v[144:147], v[120:123], v[132:135], v[144:147]
	v_mfma_f32_16x16x32_bf16 v[108:111], v[112:115], v[162:165], v[108:111]
	v_mfma_f32_16x16x32_bf16 v[104:107], v[120:123], v[162:165], v[104:107]
	v_mfma_f32_16x16x32_bf16 v[92:95], v[112:115], v[170:173], v[92:95]
	v_mfma_f32_16x16x32_bf16 v[88:91], v[120:123], v[170:173], v[88:91]
	v_mfma_f32_16x16x32_bf16 v[76:79], v[112:115], v[204:207], v[76:79]
	v_mfma_f32_16x16x32_bf16 v[72:75], v[120:123], v[204:207], v[72:75]
	v_mfma_f32_16x16x32_bf16 v[148:151], v[116:119], v[136:139], v[148:151]
	v_mfma_f32_16x16x32_bf16 v[144:147], v[124:127], v[136:139], v[144:147]
	v_mfma_f32_16x16x32_bf16 v[108:111], v[116:119], v[166:169], v[108:111]
	v_mfma_f32_16x16x32_bf16 v[104:107], v[124:127], v[166:169], v[104:107]
	v_mfma_f32_16x16x32_bf16 v[92:95], v[116:119], v[200:203], v[92:95]
	v_mfma_f32_16x16x32_bf16 v[88:91], v[124:127], v[200:203], v[88:91]
	v_mfma_f32_16x16x32_bf16 v[76:79], v[116:119], v[208:211], v[76:79]
	v_mfma_f32_16x16x32_bf16 v[72:75], v[124:127], v[208:211], v[72:75]
	s_barrier
	s_add_i32 s50, 0, 0x1c000
	s_add_i32 s21, s21, s54
	v_add_u32_e32 v231, s50, v175
	s_mov_b32 m0, s21
	ds_read_b128 v[212:215], v231
	ds_read_b128 v[216:219], v231 offset:1024
	ds_read_b128 v[232:235], v231 offset:2048
	ds_read_b128 v[236:239], v231 offset:3072
	global_load_lds_dwordx4 v176, s[72:73]
	s_add_i32 m0, s21, 0x2000
	s_nop 0
	global_load_lds_dwordx4 v152, s[72:73]
	s_barrier
	s_waitcnt lgkmcnt(0)
	v_mfma_f32_16x16x32_bf16 v[140:143], v[212:215], v[132:135], v[140:143]
	v_mfma_f32_16x16x32_bf16 v[128:131], v[232:235], v[132:135], v[128:131]
	v_mfma_f32_16x16x32_bf16 v[100:103], v[212:215], v[162:165], v[100:103]
	v_mfma_f32_16x16x32_bf16 v[96:99], v[232:235], v[162:165], v[96:99]
	v_mfma_f32_16x16x32_bf16 v[84:87], v[212:215], v[170:173], v[84:87]
	v_mfma_f32_16x16x32_bf16 v[80:83], v[232:235], v[170:173], v[80:83]
	v_mfma_f32_16x16x32_bf16 v[68:71], v[212:215], v[204:207], v[68:71]
	v_mfma_f32_16x16x32_bf16 v[64:67], v[232:235], v[204:207], v[64:67]
	v_mfma_f32_16x16x32_bf16 v[140:143], v[216:219], v[136:139], v[140:143]
	v_mfma_f32_16x16x32_bf16 v[136:139], v[236:239], v[136:139], v[128:131]
	v_mfma_f32_16x16x32_bf16 v[100:103], v[216:219], v[166:169], v[100:103]
	v_mfma_f32_16x16x32_bf16 v[96:99], v[236:239], v[166:169], v[96:99]
	v_mfma_f32_16x16x32_bf16 v[84:87], v[216:219], v[200:203], v[84:87]
	v_mfma_f32_16x16x32_bf16 v[80:83], v[236:239], v[200:203], v[80:83]
	v_mfma_f32_16x16x32_bf16 v[68:71], v[216:219], v[208:211], v[68:71]
	v_mfma_f32_16x16x32_bf16 v[64:67], v[236:239], v[208:211], v[64:67]
	s_mov_b32 m0, s7
	s_barrier
	ds_read_b128 v[128:131], v199 offset:49152
	ds_read_b128 v[132:135], v199 offset:50176
	ds_read_b128 v[162:165], v199 offset:51200
	ds_read_b128 v[166:169], v199 offset:52224
	ds_read_b128 v[170:173], v199 offset:53248
	ds_read_b128 v[200:203], v199 offset:54272
	ds_read_b128 v[204:207], v199 offset:55296
	ds_read_b128 v[208:211], v199 offset:56320
	global_load_lds_dwordx4 v156, s[94:95]
	s_mov_b32 m0, s15
	s_nop 0
	global_load_lds_dwordx4 v154, s[94:95]
	s_barrier
	s_waitcnt lgkmcnt(0)
	v_mfma_f32_16x16x32_bf16 v[60:63], v[112:115], v[128:131], v[60:63]
	v_mfma_f32_16x16x32_bf16 v[56:59], v[120:123], v[128:131], v[56:59]
	v_mfma_f32_16x16x32_bf16 v[44:47], v[112:115], v[162:165], v[44:47]
	v_mfma_f32_16x16x32_bf16 v[40:43], v[120:123], v[162:165], v[40:43]
	v_mfma_f32_16x16x32_bf16 v[28:31], v[112:115], v[170:173], v[28:31]
	v_mfma_f32_16x16x32_bf16 v[24:27], v[120:123], v[170:173], v[24:27]
	v_mfma_f32_16x16x32_bf16 v[12:15], v[112:115], v[204:207], v[12:15]
	v_mfma_f32_16x16x32_bf16 v[8:11], v[120:123], v[204:207], v[8:11]
	v_mfma_f32_16x16x32_bf16 v[60:63], v[116:119], v[132:135], v[60:63]
	v_mfma_f32_16x16x32_bf16 v[56:59], v[124:127], v[132:135], v[56:59]
	v_mfma_f32_16x16x32_bf16 v[44:47], v[116:119], v[166:169], v[44:47]
	v_mfma_f32_16x16x32_bf16 v[40:43], v[124:127], v[166:169], v[40:43]
	v_mfma_f32_16x16x32_bf16 v[28:31], v[116:119], v[200:203], v[28:31]
	v_mfma_f32_16x16x32_bf16 v[24:27], v[124:127], v[200:203], v[24:27]
	v_mfma_f32_16x16x32_bf16 v[12:15], v[116:119], v[208:211], v[12:15]
	v_mfma_f32_16x16x32_bf16 v[8:11], v[124:127], v[208:211], v[8:11]
	s_barrier
	s_add_u32 s28, s28, 0x100080
	s_addc_u32 s29, s29, 0
	s_add_i32 s21, s50, s54
	s_mov_b32 m0, s21
	s_nop 0
	global_load_lds_dwordx4 v176, s[28:29]
	s_add_i32 m0, s21, 0x2000
	s_nop 0
	global_load_lds_dwordx4 v152, s[28:29]
	s_waitcnt vmcnt(6)
	s_barrier
	v_mfma_f32_16x16x32_bf16 v[52:55], v[212:215], v[128:131], v[52:55]
	v_mfma_f32_16x16x32_bf16 v[48:51], v[232:235], v[128:131], v[48:51]
	v_mfma_f32_16x16x32_bf16 v[36:39], v[212:215], v[162:165], v[36:39]
	v_mfma_f32_16x16x32_bf16 v[32:35], v[232:235], v[162:165], v[32:35]
	v_mfma_f32_16x16x32_bf16 v[20:23], v[212:215], v[170:173], v[20:23]
	v_mfma_f32_16x16x32_bf16 v[16:19], v[232:235], v[170:173], v[16:19]
	v_mfma_f32_16x16x32_bf16 v[4:7], v[212:215], v[204:207], v[4:7]
	v_mfma_f32_16x16x32_bf16 v[0:3], v[232:235], v[204:207], v[0:3]
	v_mfma_f32_16x16x32_bf16 v[52:55], v[216:219], v[132:135], v[52:55]
	v_mfma_f32_16x16x32_bf16 v[48:51], v[236:239], v[132:135], v[48:51]
	v_mfma_f32_16x16x32_bf16 v[36:39], v[216:219], v[166:169], v[36:39]
	v_mfma_f32_16x16x32_bf16 v[32:35], v[236:239], v[166:169], v[32:35]
	v_mfma_f32_16x16x32_bf16 v[20:23], v[216:219], v[200:203], v[20:23]
	v_mfma_f32_16x16x32_bf16 v[16:19], v[236:239], v[200:203], v[16:19]
	v_mfma_f32_16x16x32_bf16 v[4:7], v[216:219], v[208:211], v[4:7]
	v_mfma_f32_16x16x32_bf16 v[0:3], v[236:239], v[208:211], v[0:3]
	s_add_i32 s20, s20, 2
	s_add_u32 s48, s48, 0x100
	s_addc_u32 s49, s49, 0
	s_add_u32 vcc_lo, vcc_lo, 0x100
	s_addc_u32 vcc_hi, vcc_hi, 0
	s_cmp_gt_u32 s20, 61
	s_barrier
	s_cbranch_scc0 .LBB0_100
	v_lshl_or_b32 v162, s34, 8, v198
	v_lshl_add_u32 v166, s2, 8, v174
	v_ashrrev_i32_e32 v163, 31, v162
	v_lshlrev_b64 v[184:185], 1, v[162:163]
	v_ashrrev_i32_e32 v167, 31, v166
	v_lshl_add_u64 v[164:165], s[68:69], 0, v[184:185]
	v_lshlrev_b64 v[192:193], 11, v[166:167]
	v_lshl_add_u64 v[112:113], v[164:165], 0, v[192:193]
	global_load_dwordx4 v[200:203], v[112:113], off
	global_load_dwordx4 v[204:207], v[112:113], off offset:256
	v_or_b32_e32 v172, 16, v166
	v_ashrrev_i32_e32 v173, 31, v172
	v_lshlrev_b64 v[112:113], 11, v[172:173]
	v_or_b32_e32 v170, 32, v166
	v_lshl_add_u64 v[112:113], v[164:165], 0, v[112:113]
	v_ashrrev_i32_e32 v171, 31, v170
	global_load_dwordx4 v[132:135], v[112:113], off
	global_load_dwordx4 v[128:131], v[112:113], off offset:256
	v_lshlrev_b64 v[112:113], 11, v[170:171]
	v_or_b32_e32 v168, 48, v166
	v_lshl_add_u64 v[112:113], v[164:165], 0, v[112:113]
	v_ashrrev_i32_e32 v169, 31, v168
	global_load_dwordx4 v[124:127], v[112:113], off
	global_load_dwordx4 v[120:123], v[112:113], off offset:256
	v_lshlrev_b64 v[112:113], 11, v[168:169]
	v_lshl_add_u64 v[112:113], v[164:165], 0, v[112:113]
	global_load_dwordx4 v[116:119], v[112:113], off
	s_nop 0
	global_load_dwordx4 v[112:115], v[112:113], off offset:256
	v_add_u32_e32 v214, 0x80, v166
	v_ashrrev_i32_e32 v215, 31, v214
	v_lshlrev_b64 v[214:215], 11, v[214:215]
	v_lshl_add_u64 v[214:215], v[164:165], 0, v[214:215]
	global_load_dwordx4 v[208:211], v[214:215], off
	s_nop 0
	global_load_dwordx4 v[212:215], v[214:215], off offset:256
	v_add_u32_e32 v234, 0x90, v166
	v_ashrrev_i32_e32 v235, 31, v234
	v_lshlrev_b64 v[234:235], 11, v[234:235]
	v_lshl_add_u64 v[234:235], v[164:165], 0, v[234:235]
	global_load_dwordx4 v[216:219], v[234:235], off
	s_nop 0
	global_load_dwordx4 v[232:235], v[234:235], off offset:256
	v_add_u32_e32 v242, 0xa0, v166
	v_ashrrev_i32_e32 v243, 31, v242
	v_lshlrev_b64 v[242:243], 11, v[242:243]
	v_lshl_add_u64 v[242:243], v[164:165], 0, v[242:243]
	global_load_dwordx4 v[236:239], v[242:243], off
	s_nop 0
	global_load_dwordx4 v[240:243], v[242:243], off offset:256
	v_add_u32_e32 v250, 0xb0, v166
	v_ashrrev_i32_e32 v251, 31, v250
	v_lshlrev_b64 v[250:251], 11, v[250:251]
	v_lshl_add_u64 v[250:251], v[164:165], 0, v[250:251]
	global_load_dwordx4 v[244:247], v[250:251], off
	s_nop 0
	global_load_dwordx4 v[248:251], v[250:251], off offset:256
	s_lshl_b32 s48, s34, 2
	s_ashr_i32 s49, s48, 31
	s_waitcnt vmcnt(8)
	v_lshlrev_b32_e32 v194, 16, v200
	v_add_f32_e32 v148, v148, v194
	v_and_b32_e32 v194, 0xffff0000, v200
	v_add_f32_e32 v149, v149, v194
	v_lshlrev_b32_e32 v194, 16, v201
	v_add_f32_e32 v150, v150, v194
	v_and_b32_e32 v194, 0xffff0000, v201
	v_add_f32_e32 v151, v151, v194
	v_lshlrev_b32_e32 v194, 16, v202
	v_add_f32_e32 v194, v144, v194
	v_and_b32_e32 v144, 0xffff0000, v202
	v_add_f32_e32 v195, v145, v144
	v_lshlrev_b32_e32 v144, 16, v203
	v_add_f32_e32 v200, v146, v144
	v_and_b32_e32 v144, 0xffff0000, v203
	v_add_f32_e32 v147, v147, v144
	v_mul_f32_e32 v144, v194, v194
	v_mul_f32_e32 v145, v195, v195
	v_fmac_f32_e32 v144, v148, v148
	v_fmac_f32_e32 v145, v149, v149
	v_add_f32_e32 v144, v144, v145
	v_mul_f32_e32 v145, v200, v200
	v_fmac_f32_e32 v145, v150, v150
	v_add_f32_e32 v144, v145, v144
	v_mul_f32_e32 v145, v147, v147
	v_fmac_f32_e32 v145, v151, v151
	v_add_f32_e32 v201, v145, v144
	v_cvt_pk_bf16_f32 v144, v148, v149
	v_lshl_add_u64 v[148:149], s[64:65], 0, v[192:193]
	v_lshl_add_u64 v[148:149], v[148:149], 0, v[184:185]
	v_cvt_pk_bf16_f32 v145, v150, v151
	v_cvt_pk_bf16_f32 v146, v194, v195
	v_cvt_pk_bf16_f32 v147, v200, v147
	global_store_dwordx4 v[148:149], v[144:147], off
	s_nop 1
	v_lshlrev_b32_e32 v144, 16, v204
	v_add_f32_e32 v140, v140, v144
	v_and_b32_e32 v144, 0xffff0000, v204
	v_add_f32_e32 v141, v141, v144
	v_lshlrev_b32_e32 v144, 16, v205
	v_add_f32_e32 v142, v142, v144
	v_and_b32_e32 v144, 0xffff0000, v205
	v_add_f32_e32 v143, v143, v144
	v_lshlrev_b32_e32 v144, 16, v206
	v_add_f32_e32 v144, v136, v144
	v_and_b32_e32 v136, 0xffff0000, v206
	v_add_f32_e32 v145, v137, v136
	v_lshlrev_b32_e32 v136, 16, v207
	v_add_f32_e32 v146, v138, v136
	v_and_b32_e32 v136, 0xffff0000, v207
	v_add_f32_e32 v139, v139, v136
	v_mul_f32_e32 v136, v144, v144
	v_fmac_f32_e32 v136, v140, v140
	v_mul_f32_e32 v137, v145, v145
	v_add_f32_e32 v136, v136, v201
	v_fmac_f32_e32 v137, v141, v141
	v_add_f32_e32 v136, v137, v136
	v_mul_f32_e32 v137, v146, v146
	v_fmac_f32_e32 v137, v142, v142
	v_add_f32_e32 v136, v137, v136
	v_mul_f32_e32 v137, v139, v139
	v_fmac_f32_e32 v137, v143, v143
	v_add_f32_e32 v147, v137, v136
	v_cvt_pk_bf16_f32 v136, v140, v141
	v_cvt_pk_bf16_f32 v137, v142, v143
	v_cvt_pk_bf16_f32 v138, v144, v145
	v_cvt_pk_bf16_f32 v139, v146, v139
	global_store_dwordx4 v[148:149], v[136:139], off offset:256
	s_nop 1
	v_and_b32_e32 v137, 64, v225
	v_xor_b32_e32 v136, 16, v225
	v_add_u32_e32 v137, 64, v137
	v_cmp_lt_i32_e32 vcc, v136, v137
	v_xor_b32_e32 v139, 32, v225
	s_nop 0
	v_cndmask_b32_e32 v136, v225, v136, vcc
	v_lshlrev_b32_e32 v136, 2, v136
	ds_bpermute_b32 v138, v136, v147
	v_cmp_lt_i32_e32 vcc, v139, v137
	s_waitcnt lgkmcnt(0)
	v_add_f32_e32 v138, v147, v138
	v_cndmask_b32_e32 v137, v225, v139, vcc
	v_lshlrev_b32_e32 v137, 2, v137
	ds_bpermute_b32 v139, v137, v138
	s_and_saveexec_b64 s[28:29], s[38:39]
	s_cbranch_execz .LBB0_103
	v_lshlrev_b64 v[140:141], 6, v[166:167]
	v_lshl_add_u64 v[140:141], s[62:63], 0, v[140:141]
	v_lshl_add_u64 v[140:141], s[48:49], 2, v[140:141]
	s_lshl_b32 s34, s9, 2
	v_lshl_add_u64 v[140:141], v[140:141], 0, s[34:35]
	s_waitcnt lgkmcnt(0)
	v_add_f32_e32 v138, v138, v139
	global_store_dword v[140:141], v138, off

.LBB0_147:
	s_add_u32 s21, s0, 0xfffc0080
	s_addc_u32 s28, s1, -1
	s_add_i32 s60, 0, 0x10000
	v_add_u32_e32 v140, s60, v205
	ds_read_b128 v[128:131], v140
	ds_read_b128 v[132:135], v140 offset:1024
	ds_read_b128 v[136:139], v140 offset:2048
	ds_read_b128 v[140:143], v140 offset:3072
	s_cmp_eq_u32 s20, 12
	s_cselect_b32 s49, s43, s28
	s_cselect_b32 s48, s24, s21
	s_cselect_b32 s29, s25, vcc_hi
	s_cselect_b32 s28, s41, vcc_lo
	s_add_i32 m0, s57, 0xc000
	ds_read_b128 v[154:157], v208
	ds_read_b128 v[158:161], v208 offset:1024
	ds_read_b128 v[162:165], v208 offset:2048
	ds_read_b128 v[166:169], v208 offset:3072
	ds_read_b128 v[170:173], v208 offset:4096
	ds_read_b128 v[198:201], v208 offset:5120
	ds_read_b128 v[210:213], v208 offset:6144
	ds_read_b128 v[214:217], v208 offset:7168
	global_load_lds_dwordx4 v150, s[0:1]
	s_add_i32 m0, s57, 0xe000
	s_nop 0
	global_load_lds_dwordx4 v152, s[0:1]
	s_waitcnt lgkmcnt(8)
	s_barrier
	s_waitcnt lgkmcnt(0)
	v_mfma_f32_16x16x32_bf16 v[124:127], v[128:131], v[154:157], v[124:127]
	v_mfma_f32_16x16x32_bf16 v[120:123], v[136:139], v[154:157], v[120:123]
	v_mfma_f32_16x16x32_bf16 v[108:111], v[128:131], v[162:165], v[108:111]
	v_mfma_f32_16x16x32_bf16 v[104:107], v[136:139], v[162:165], v[104:107]
	v_mfma_f32_16x16x32_bf16 v[92:95], v[128:131], v[170:173], v[92:95]
	v_mfma_f32_16x16x32_bf16 v[88:91], v[136:139], v[170:173], v[88:91]
	v_mfma_f32_16x16x32_bf16 v[76:79], v[128:131], v[210:213], v[76:79]
	v_mfma_f32_16x16x32_bf16 v[72:75], v[136:139], v[210:213], v[72:75]
	v_mfma_f32_16x16x32_bf16 v[124:127], v[132:135], v[158:161], v[124:127]
	v_mfma_f32_16x16x32_bf16 v[120:123], v[140:143], v[158:161], v[120:123]
	v_mfma_f32_16x16x32_bf16 v[108:111], v[132:135], v[166:169], v[108:111]
	v_mfma_f32_16x16x32_bf16 v[104:107], v[140:143], v[166:169], v[104:107]
	v_mfma_f32_16x16x32_bf16 v[92:95], v[132:135], v[198:201], v[92:95]
	v_mfma_f32_16x16x32_bf16 v[88:91], v[140:143], v[198:201], v[88:91]
	v_mfma_f32_16x16x32_bf16 v[76:79], v[132:135], v[214:217], v[76:79]
	v_mfma_f32_16x16x32_bf16 v[72:75], v[140:143], v[214:217], v[72:75]
	s_barrier
	s_add_i32 s21, 0, 0x14000
	v_add_u32_e32 v174, s21, v205
	s_add_i32 s60, s60, s56
	ds_read_b128 v[232:235], v174
	ds_read_b128 v[236:239], v174 offset:1024
	ds_read_b128 v[240:243], v174 offset:2048
	ds_read_b128 v[244:247], v174 offset:3072
	s_add_u32 s72, s28, s52
	s_addc_u32 s73, s29, s53
	s_mov_b32 m0, s60
	s_nop 0
	global_load_lds_dwordx4 v176, s[28:29]
	s_add_i32 m0, s60, 0x2000
	s_nop 0
	global_load_lds_dwordx4 v144, s[28:29]
	s_barrier
	s_waitcnt lgkmcnt(0)
	v_mfma_f32_16x16x32_bf16 v[116:119], v[232:235], v[154:157], v[116:119]
	v_mfma_f32_16x16x32_bf16 v[112:115], v[240:243], v[154:157], v[112:115]
	v_mfma_f32_16x16x32_bf16 v[100:103], v[232:235], v[162:165], v[100:103]
	v_mfma_f32_16x16x32_bf16 v[96:99], v[240:243], v[162:165], v[96:99]
	v_mfma_f32_16x16x32_bf16 v[84:87], v[232:235], v[170:173], v[84:87]
	v_mfma_f32_16x16x32_bf16 v[80:83], v[240:243], v[170:173], v[80:83]
	v_mfma_f32_16x16x32_bf16 v[68:71], v[232:235], v[210:213], v[68:71]
	v_mfma_f32_16x16x32_bf16 v[64:67], v[240:243], v[210:213], v[64:67]
	v_mfma_f32_16x16x32_bf16 v[116:119], v[236:239], v[158:161], v[116:119]
	v_mfma_f32_16x16x32_bf16 v[112:115], v[244:247], v[158:161], v[112:115]
	v_mfma_f32_16x16x32_bf16 v[100:103], v[236:239], v[166:169], v[100:103]
	v_mfma_f32_16x16x32_bf16 v[96:99], v[244:247], v[166:169], v[96:99]
	v_mfma_f32_16x16x32_bf16 v[84:87], v[236:239], v[198:201], v[84:87]
	v_mfma_f32_16x16x32_bf16 v[80:83], v[244:247], v[198:201], v[80:83]
	v_mfma_f32_16x16x32_bf16 v[68:71], v[236:239], v[214:217], v[68:71]
	v_mfma_f32_16x16x32_bf16 v[64:67], v[244:247], v[214:217], v[64:67]
	s_mov_b32 m0, s57
	s_add_u32 s94, s48, s52
	s_addc_u32 s95, s49, s53
	s_barrier
	ds_read_b128 v[154:157], v208 offset:16384
	ds_read_b128 v[158:161], v208 offset:17408
	ds_read_b128 v[162:165], v208 offset:18432
	ds_read_b128 v[166:169], v208 offset:19456
	ds_read_b128 v[170:173], v208 offset:20480
	ds_read_b128 v[198:201], v208 offset:21504
	ds_read_b128 v[210:213], v208 offset:22528
	ds_read_b128 v[214:217], v208 offset:23552
	global_load_lds_dwordx4 v148, s[48:49]
	s_mov_b32 m0, s58
	s_nop 0
	global_load_lds_dwordx4 v146, s[48:49]
	s_barrier
	s_waitcnt lgkmcnt(0)
	v_mfma_f32_16x16x32_bf16 v[60:63], v[128:131], v[154:157], v[60:63]
	v_mfma_f32_16x16x32_bf16 v[56:59], v[136:139], v[154:157], v[56:59]
	v_mfma_f32_16x16x32_bf16 v[44:47], v[128:131], v[162:165], v[44:47]
	v_mfma_f32_16x16x32_bf16 v[40:43], v[136:139], v[162:165], v[40:43]
	v_mfma_f32_16x16x32_bf16 v[28:31], v[128:131], v[170:173], v[28:31]
	v_mfma_f32_16x16x32_bf16 v[24:27], v[136:139], v[170:173], v[24:27]
	v_mfma_f32_16x16x32_bf16 v[12:15], v[128:131], v[210:213], v[12:15]
	v_mfma_f32_16x16x32_bf16 v[8:11], v[136:139], v[210:213], v[8:11]
	v_mfma_f32_16x16x32_bf16 v[60:63], v[132:135], v[158:161], v[60:63]
	v_mfma_f32_16x16x32_bf16 v[56:59], v[140:143], v[158:161], v[56:59]
	v_mfma_f32_16x16x32_bf16 v[44:47], v[132:135], v[166:169], v[44:47]
	v_mfma_f32_16x16x32_bf16 v[40:43], v[140:143], v[166:169], v[40:43]
	v_mfma_f32_16x16x32_bf16 v[28:31], v[132:135], v[198:201], v[28:31]
	v_mfma_f32_16x16x32_bf16 v[24:27], v[140:143], v[198:201], v[24:27]
	v_mfma_f32_16x16x32_bf16 v[12:15], v[132:135], v[214:217], v[12:15]
	v_mfma_f32_16x16x32_bf16 v[8:11], v[140:143], v[214:217], v[8:11]
	s_barrier
	s_add_u32 s60, s28, 0x40000
	s_addc_u32 s61, s29, 0
	s_add_i32 s21, s21, s56
	s_mov_b32 m0, s21
	s_nop 0
	global_load_lds_dwordx4 v176, s[60:61]
	s_add_i32 m0, s21, 0x2000
	s_nop 0
	global_load_lds_dwordx4 v144, s[60:61]
	s_waitcnt vmcnt(6)
	s_barrier
	v_mfma_f32_16x16x32_bf16 v[52:55], v[232:235], v[154:157], v[52:55]
	v_mfma_f32_16x16x32_bf16 v[48:51], v[240:243], v[154:157], v[48:51]
	v_mfma_f32_16x16x32_bf16 v[36:39], v[232:235], v[162:165], v[36:39]
	v_mfma_f32_16x16x32_bf16 v[32:35], v[240:243], v[162:165], v[32:35]
	v_mfma_f32_16x16x32_bf16 v[20:23], v[232:235], v[170:173], v[20:23]
	v_mfma_f32_16x16x32_bf16 v[16:19], v[240:243], v[170:173], v[16:19]
	v_mfma_f32_16x16x32_bf16 v[4:7], v[232:235], v[210:213], v[4:7]
	v_mfma_f32_16x16x32_bf16 v[0:3], v[240:243], v[210:213], v[0:3]
	v_mfma_f32_16x16x32_bf16 v[52:55], v[236:239], v[158:161], v[52:55]
	v_mfma_f32_16x16x32_bf16 v[48:51], v[244:247], v[158:161], v[48:51]
	v_mfma_f32_16x16x32_bf16 v[36:39], v[236:239], v[166:169], v[36:39]
	v_mfma_f32_16x16x32_bf16 v[32:35], v[244:247], v[166:169], v[32:35]
	v_mfma_f32_16x16x32_bf16 v[20:23], v[236:239], v[198:201], v[20:23]
	v_mfma_f32_16x16x32_bf16 v[16:19], v[244:247], v[198:201], v[16:19]
	v_mfma_f32_16x16x32_bf16 v[4:7], v[236:239], v[214:217], v[4:7]
	v_mfma_f32_16x16x32_bf16 v[0:3], v[244:247], v[214:217], v[0:3]
	s_add_i32 s21, 0, 0x18000
	v_add_u32_e32 v140, s21, v205
	s_barrier
	ds_read_b128 v[128:131], v140
	ds_read_b128 v[132:135], v140 offset:1024
	ds_read_b128 v[136:139], v140 offset:2048
	ds_read_b128 v[140:143], v140 offset:3072
	s_add_u32 s48, s48, 0x40000
	s_addc_u32 s49, s49, 0
	s_mov_b32 m0, s7
	ds_read_b128 v[154:157], v208 offset:32768
	ds_read_b128 v[158:161], v208 offset:33792
	ds_read_b128 v[162:165], v208 offset:34816
	ds_read_b128 v[166:169], v208 offset:35840
	ds_read_b128 v[170:173], v208 offset:36864
	ds_read_b128 v[198:201], v208 offset:37888
	ds_read_b128 v[210:213], v208 offset:38912
	ds_read_b128 v[214:217], v208 offset:39936
	global_load_lds_dwordx4 v148, s[48:49]
	s_mov_b32 m0, s15
	s_nop 0
	global_load_lds_dwordx4 v146, s[48:49]
	s_waitcnt lgkmcnt(8)
	s_barrier
	s_waitcnt lgkmcnt(0)
	v_mfma_f32_16x16x32_bf16 v[124:127], v[128:131], v[154:157], v[124:127]
	v_mfma_f32_16x16x32_bf16 v[120:123], v[136:139], v[154:157], v[120:123]
	v_mfma_f32_16x16x32_bf16 v[108:111], v[128:131], v[162:165], v[108:111]
	v_mfma_f32_16x16x32_bf16 v[104:107], v[136:139], v[162:165], v[104:107]
	v_mfma_f32_16x16x32_bf16 v[92:95], v[128:131], v[170:173], v[92:95]
	v_mfma_f32_16x16x32_bf16 v[88:91], v[136:139], v[170:173], v[88:91]
	v_mfma_f32_16x16x32_bf16 v[76:79], v[128:131], v[210:213], v[76:79]
	v_mfma_f32_16x16x32_bf16 v[72:75], v[136:139], v[210:213], v[72:75]
	v_mfma_f32_16x16x32_bf16 v[124:127], v[132:135], v[158:161], v[124:127]
	v_mfma_f32_16x16x32_bf16 v[120:123], v[140:143], v[158:161], v[120:123]
	v_mfma_f32_16x16x32_bf16 v[108:111], v[132:135], v[166:169], v[108:111]
	v_mfma_f32_16x16x32_bf16 v[104:107], v[140:143], v[166:169], v[104:107]
	v_mfma_f32_16x16x32_bf16 v[92:95], v[132:135], v[198:201], v[92:95]
	v_mfma_f32_16x16x32_bf16 v[88:91], v[140:143], v[198:201], v[88:91]
	v_mfma_f32_16x16x32_bf16 v[76:79], v[132:135], v[214:217], v[76:79]
	v_mfma_f32_16x16x32_bf16 v[72:75], v[140:143], v[214:217], v[72:75]
	s_barrier
	s_add_i32 s48, 0, 0x1c000
	s_add_i32 s21, s21, s56
	v_add_u32_e32 v202, s48, v205
	s_mov_b32 m0, s21
	ds_read_b128 v[232:235], v202
	ds_read_b128 v[236:239], v202 offset:1024
	ds_read_b128 v[240:243], v202 offset:2048
	ds_read_b128 v[244:247], v202 offset:3072
	global_load_lds_dwordx4 v176, s[72:73]
	s_add_i32 m0, s21, 0x2000
	s_nop 0
	global_load_lds_dwordx4 v144, s[72:73]
	s_barrier
	s_waitcnt lgkmcnt(0)
	v_mfma_f32_16x16x32_bf16 v[116:119], v[232:235], v[154:157], v[116:119]
	v_mfma_f32_16x16x32_bf16 v[112:115], v[240:243], v[154:157], v[112:115]
	v_mfma_f32_16x16x32_bf16 v[100:103], v[232:235], v[162:165], v[100:103]
	v_mfma_f32_16x16x32_bf16 v[96:99], v[240:243], v[162:165], v[96:99]
	v_mfma_f32_16x16x32_bf16 v[84:87], v[232:235], v[170:173], v[84:87]
	v_mfma_f32_16x16x32_bf16 v[80:83], v[240:243], v[170:173], v[80:83]
	v_mfma_f32_16x16x32_bf16 v[68:71], v[232:235], v[210:213], v[68:71]
	v_mfma_f32_16x16x32_bf16 v[64:67], v[240:243], v[210:213], v[64:67]
	v_mfma_f32_16x16x32_bf16 v[116:119], v[236:239], v[158:161], v[116:119]
	v_mfma_f32_16x16x32_bf16 v[112:115], v[244:247], v[158:161], v[112:115]
	v_mfma_f32_16x16x32_bf16 v[100:103], v[236:239], v[166:169], v[100:103]
	v_mfma_f32_16x16x32_bf16 v[96:99], v[244:247], v[166:169], v[96:99]
	v_mfma_f32_16x16x32_bf16 v[84:87], v[236:239], v[198:201], v[84:87]
	v_mfma_f32_16x16x32_bf16 v[80:83], v[244:247], v[198:201], v[80:83]
	v_mfma_f32_16x16x32_bf16 v[68:71], v[236:239], v[214:217], v[68:71]
	v_mfma_f32_16x16x32_bf16 v[64:67], v[244:247], v[214:217], v[64:67]
	s_mov_b32 m0, s3
	s_barrier
	ds_read_b128 v[154:157], v208 offset:49152
	ds_read_b128 v[158:161], v208 offset:50176
	ds_read_b128 v[162:165], v208 offset:51200
	ds_read_b128 v[166:169], v208 offset:52224
	ds_read_b128 v[170:173], v208 offset:53248
	ds_read_b128 v[198:201], v208 offset:54272
	ds_read_b128 v[210:213], v208 offset:55296
	ds_read_b128 v[214:217], v208 offset:56320
	global_load_lds_dwordx4 v148, s[94:95]
	s_mov_b32 m0, s6
	s_nop 0
	global_load_lds_dwordx4 v146, s[94:95]
	s_barrier
	s_waitcnt lgkmcnt(0)
	v_mfma_f32_16x16x32_bf16 v[60:63], v[128:131], v[154:157], v[60:63]
	v_mfma_f32_16x16x32_bf16 v[56:59], v[136:139], v[154:157], v[56:59]
	v_mfma_f32_16x16x32_bf16 v[44:47], v[128:131], v[162:165], v[44:47]
	v_mfma_f32_16x16x32_bf16 v[40:43], v[136:139], v[162:165], v[40:43]
	v_mfma_f32_16x16x32_bf16 v[28:31], v[128:131], v[170:173], v[28:31]
	v_mfma_f32_16x16x32_bf16 v[24:27], v[136:139], v[170:173], v[24:27]
	v_mfma_f32_16x16x32_bf16 v[12:15], v[128:131], v[210:213], v[12:15]
	v_mfma_f32_16x16x32_bf16 v[8:11], v[136:139], v[210:213], v[8:11]
	v_mfma_f32_16x16x32_bf16 v[60:63], v[132:135], v[158:161], v[60:63]
	v_mfma_f32_16x16x32_bf16 v[56:59], v[140:143], v[158:161], v[56:59]
	v_mfma_f32_16x16x32_bf16 v[44:47], v[132:135], v[166:169], v[44:47]
	v_mfma_f32_16x16x32_bf16 v[40:43], v[140:143], v[166:169], v[40:43]
	v_mfma_f32_16x16x32_bf16 v[28:31], v[132:135], v[198:201], v[28:31]
	v_mfma_f32_16x16x32_bf16 v[24:27], v[140:143], v[198:201], v[24:27]
	v_mfma_f32_16x16x32_bf16 v[12:15], v[132:135], v[214:217], v[12:15]
	v_mfma_f32_16x16x32_bf16 v[8:11], v[140:143], v[214:217], v[8:11]
	s_barrier
	s_add_u32 s28, s28, 0x40080
	s_addc_u32 s29, s29, 0
	s_add_i32 s21, s48, s56
	s_mov_b32 m0, s21
	s_nop 0
	global_load_lds_dwordx4 v176, s[28:29]
	s_add_i32 m0, s21, 0x2000
	s_nop 0
	global_load_lds_dwordx4 v144, s[28:29]
	s_waitcnt vmcnt(6)
	s_barrier
	v_mfma_f32_16x16x32_bf16 v[52:55], v[232:235], v[154:157], v[52:55]
	v_mfma_f32_16x16x32_bf16 v[48:51], v[240:243], v[154:157], v[48:51]
	v_mfma_f32_16x16x32_bf16 v[36:39], v[232:235], v[162:165], v[36:39]
	v_mfma_f32_16x16x32_bf16 v[32:35], v[240:243], v[162:165], v[32:35]
	v_mfma_f32_16x16x32_bf16 v[20:23], v[232:235], v[170:173], v[20:23]
	v_mfma_f32_16x16x32_bf16 v[16:19], v[240:243], v[170:173], v[16:19]
	v_mfma_f32_16x16x32_bf16 v[4:7], v[232:235], v[210:213], v[4:7]
	v_mfma_f32_16x16x32_bf16 v[0:3], v[240:243], v[210:213], v[0:3]
	v_mfma_f32_16x16x32_bf16 v[52:55], v[236:239], v[158:161], v[52:55]
	v_mfma_f32_16x16x32_bf16 v[48:51], v[244:247], v[158:161], v[48:51]
	v_mfma_f32_16x16x32_bf16 v[36:39], v[236:239], v[166:169], v[36:39]
	v_mfma_f32_16x16x32_bf16 v[32:35], v[244:247], v[166:169], v[32:35]
	v_mfma_f32_16x16x32_bf16 v[20:23], v[236:239], v[198:201], v[20:23]
	v_mfma_f32_16x16x32_bf16 v[16:19], v[244:247], v[198:201], v[16:19]
	v_mfma_f32_16x16x32_bf16 v[4:7], v[236:239], v[214:217], v[4:7]
	v_mfma_f32_16x16x32_bf16 v[0:3], v[244:247], v[214:217], v[0:3]
	s_add_i32 s20, s20, 2
	s_add_u32 s0, s0, 0x100
	s_addc_u32 s1, s1, 0
	s_add_u32 vcc_lo, vcc_lo, 0x100
	s_addc_u32 vcc_hi, vcc_hi, 0
	s_cmp_gt_u32 s20, 13
	s_barrier
	s_cbranch_scc0 .LBB0_147
	s_cmp_eq_u32 s2, s51
	s_cselect_b64 s[48:49], -1, 0
	s_cmp_eq_u32 s2, s50
	v_lshl_add_u32 v170, s2, 8, v204
	s_cselect_b64 s[0:1], -1, 0
	s_or_b64 s[20:21], s[48:49], s[0:1]
	v_or_b32_e32 v166, 16, v170
	v_or_b32_e32 v164, 32, v170
	v_or_b32_e32 v162, 48, v170
	v_add_u32_e32 v160, 0x80, v170
	v_add_u32_e32 v158, 0x90, v170
	v_add_u32_e32 v156, 0xa0, v170
	v_add_u32_e32 v154, 0xb0, v170
	s_mov_b64 s[0:1], -1
	s_and_b64 vcc, exec, s[20:21]
	v_ashrrev_i32_e32 v171, 31, v170
	v_ashrrev_i32_e32 v167, 31, v166
	v_ashrrev_i32_e32 v165, 31, v164
	v_ashrrev_i32_e32 v163, 31, v162
	v_ashrrev_i32_e32 v161, 31, v160
	v_ashrrev_i32_e32 v159, 31, v158
	v_ashrrev_i32_e32 v157, 31, v156
	v_ashrrev_i32_e32 v155, 31, v154
	s_cbranch_vccnz .LBB0_150
	v_readlane_b32 s20, v253, 31
	v_lshlrev_b64 v[128:129], 6, v[170:171]
	v_readlane_b32 s21, v253, 32
	s_mov_b32 s0, 0x3727c5ac
	v_mov_b64_e32 v[198:199], s[0:1]
	v_lshl_add_u64 v[140:141], s[20:21], 0, v[128:129]
	global_load_dwordx4 v[128:131], v[140:141], off offset:32
	global_load_dwordx4 v[132:135], v[140:141], off offset:48
	global_load_dwordx4 v[136:139], v[140:141], off
	s_nop 0
	global_load_dwordx4 v[140:143], v[140:141], off offset:16
	s_mov_b32 s2, 0x3a800000
	s_mov_b32 s24, 0x45800000
	s_waitcnt vmcnt(0)
	v_pk_add_f32 v[128:129], v[128:129], v[132:133]
	v_pk_add_f32 v[130:131], v[130:131], v[134:135]
	v_pk_add_f32 v[136:137], v[136:137], v[140:141]
	v_pk_add_f32 v[138:139], v[138:139], v[142:143]
	v_pk_add_f32 v[172:173], v[136:137], v[128:129]
	v_lshlrev_b64 v[128:129], 6, v[166:167]
	v_lshl_add_u64 v[140:141], s[20:21], 0, v[128:129]
	v_pk_add_f32 v[168:169], v[138:139], v[130:131]
	global_load_dwordx4 v[128:131], v[140:141], off offset:32
	global_load_dwordx4 v[132:135], v[140:141], off offset:48
	global_load_dwordx4 v[136:139], v[140:141], off
	s_nop 0
	global_load_dwordx4 v[140:143], v[140:141], off offset:16
	s_waitcnt vmcnt(0)
	v_pk_add_f32 v[128:129], v[128:129], v[132:133]
	v_pk_add_f32 v[130:131], v[130:131], v[134:135]
	v_pk_add_f32 v[136:137], v[136:137], v[140:141]
	v_pk_add_f32 v[138:139], v[138:139], v[142:143]
	v_pk_add_f32 v[128:129], v[136:137], v[128:129]
	v_pk_add_f32 v[130:131], v[138:139], v[130:131]
	v_mov_b32_e32 v132, v128
	v_mov_b32_e32 v133, v172
	v_mov_b32_e32 v172, v129
	v_pk_add_f32 v[128:129], v[132:133], v[172:173]
	v_mov_b32_e32 v132, v130
	v_mov_b32_e32 v133, v168
	v_pk_add_f32 v[128:129], v[132:133], v[128:129]
	v_mov_b32_e32 v168, v131
	v_pk_add_f32 v[128:129], v[168:169], v[128:129]
	s_nop 0
	v_pk_fma_f32 v[128:129], v[128:129], s[2:3], v[198:199] op_sel_hi:[1,0,0]
	s_nop 0
	v_mul_f32_e32 v130, 0x4b800000, v129
	v_cmp_gt_f32_e64 s[0:1], s23, v129
	v_cmp_gt_f32_e32 vcc, s23, v128
	s_nop 0
	v_cndmask_b32_e64 v129, v129, v130, s[0:1]
	v_mul_f32_e32 v130, 0x4b800000, v128
	v_cndmask_b32_e32 v128, v128, v130, vcc
	v_rsq_f32_e32 v129, v129
	v_rsq_f32_e32 v128, v128
	s_nop 0
	v_pk_mul_f32 v[130:131], v[128:129], s[24:25] op_sel_hi:[1,0]
	s_nop 0
	v_cndmask_b32_e32 v169, v128, v130, vcc
	v_cndmask_b32_e64 v168, v129, v131, s[0:1]
	v_lshlrev_b64 v[128:129], 6, v[164:165]
	v_lshl_add_u64 v[140:141], s[20:21], 0, v[128:129]
	global_load_dwordx4 v[128:131], v[140:141], off offset:32
	global_load_dwordx4 v[132:135], v[140:141], off offset:48
	global_load_dwordx4 v[136:139], v[140:141], off
	s_nop 0
	global_load_dwordx4 v[140:143], v[140:141], off offset:16
	s_waitcnt vmcnt(0)
	v_pk_add_f32 v[128:129], v[128:129], v[132:133]
	v_pk_add_f32 v[130:131], v[130:131], v[134:135]
	v_pk_add_f32 v[136:137], v[136:137], v[140:141]
	v_pk_add_f32 v[138:139], v[138:139], v[142:143]
	v_pk_add_f32 v[174:175], v[136:137], v[128:129]
	v_lshlrev_b64 v[128:129], 6, v[162:163]
	v_lshl_add_u64 v[140:141], s[20:21], 0, v[128:129]
	v_pk_add_f32 v[172:173], v[138:139], v[130:131]
	global_load_dwordx4 v[128:131], v[140:141], off offset:32
	global_load_dwordx4 v[132:135], v[140:141], off offset:48
	global_load_dwordx4 v[136:139], v[140:141], off
	s_nop 0
	global_load_dwordx4 v[140:143], v[140:141], off offset:16
	s_waitcnt vmcnt(0)
	v_pk_add_f32 v[128:129], v[128:129], v[132:133]
	v_pk_add_f32 v[130:131], v[130:131], v[134:135]
	v_pk_add_f32 v[136:137], v[136:137], v[140:141]
	v_pk_add_f32 v[138:139], v[138:139], v[142:143]
	v_pk_add_f32 v[128:129], v[136:137], v[128:129]
	v_pk_add_f32 v[130:131], v[138:139], v[130:131]
	v_mov_b32_e32 v132, v128
	v_mov_b32_e32 v133, v174
	v_mov_b32_e32 v174, v129
	v_pk_add_f32 v[128:129], v[132:133], v[174:175]
	v_mov_b32_e32 v132, v130
	v_mov_b32_e32 v133, v172
	v_pk_add_f32 v[128:129], v[132:133], v[128:129]
	v_mov_b32_e32 v172, v131
	v_pk_add_f32 v[128:129], v[172:173], v[128:129]
	s_nop 0
	v_pk_fma_f32 v[128:129], v[128:129], s[2:3], v[198:199] op_sel_hi:[1,0,0]
	s_nop 0
	v_mul_f32_e32 v130, 0x4b800000, v129
	v_cmp_gt_f32_e64 s[0:1], s23, v129
	v_cmp_gt_f32_e32 vcc, s23, v128
	s_nop 0
	v_cndmask_b32_e64 v129, v129, v130, s[0:1]
	v_mul_f32_e32 v130, 0x4b800000, v128
	v_cndmask_b32_e32 v128, v128, v130, vcc
	v_rsq_f32_e32 v129, v129
	v_rsq_f32_e32 v128, v128
	s_nop 0
	v_pk_mul_f32 v[130:131], v[128:129], s[24:25] op_sel_hi:[1,0]
	s_nop 0
	v_cndmask_b32_e32 v173, v128, v130, vcc
	v_cndmask_b32_e64 v172, v129, v131, s[0:1]
	v_lshlrev_b64 v[128:129], 6, v[160:161]
	v_lshl_add_u64 v[140:141], s[20:21], 0, v[128:129]
	global_load_dwordx4 v[128:131], v[140:141], off offset:32
	global_load_dwordx4 v[132:135], v[140:141], off offset:48
	global_load_dwordx4 v[136:139], v[140:141], off
	s_nop 0
	global_load_dwordx4 v[140:143], v[140:141], off offset:16
	s_waitcnt vmcnt(0)
	v_pk_add_f32 v[128:129], v[128:129], v[132:133]
	v_pk_add_f32 v[130:131], v[130:131], v[134:135]
	v_pk_add_f32 v[136:137], v[136:137], v[140:141]
	v_pk_add_f32 v[138:139], v[138:139], v[142:143]
	v_pk_add_f32 v[184:185], v[136:137], v[128:129]
	v_lshlrev_b64 v[128:129], 6, v[158:159]
	v_lshl_add_u64 v[140:141], s[20:21], 0, v[128:129]
	v_pk_add_f32 v[174:175], v[138:139], v[130:131]
	global_load_dwordx4 v[128:131], v[140:141], off offset:32
	global_load_dwordx4 v[132:135], v[140:141], off offset:48
	global_load_dwordx4 v[136:139], v[140:141], off
	s_nop 0
	global_load_dwordx4 v[140:143], v[140:141], off offset:16
	s_waitcnt vmcnt(0)
	v_pk_add_f32 v[128:129], v[128:129], v[132:133]
	v_pk_add_f32 v[130:131], v[130:131], v[134:135]
	v_pk_add_f32 v[136:137], v[136:137], v[140:141]
	v_pk_add_f32 v[138:139], v[138:139], v[142:143]
	v_pk_add_f32 v[128:129], v[136:137], v[128:129]
	v_pk_add_f32 v[130:131], v[138:139], v[130:131]
	v_mov_b32_e32 v132, v128
	v_mov_b32_e32 v133, v184
	v_mov_b32_e32 v184, v129
	v_pk_add_f32 v[128:129], v[132:133], v[184:185]
	v_mov_b32_e32 v132, v130
	v_mov_b32_e32 v133, v174
	v_pk_add_f32 v[128:129], v[132:133], v[128:129]
	v_mov_b32_e32 v174, v131
	v_pk_add_f32 v[128:129], v[174:175], v[128:129]
	s_nop 0
	v_pk_fma_f32 v[128:129], v[128:129], s[2:3], v[198:199] op_sel_hi:[1,0,0]
	s_nop 0
	v_mul_f32_e32 v130, 0x4b800000, v129
	v_cmp_gt_f32_e64 s[0:1], s23, v129
	v_cmp_gt_f32_e32 vcc, s23, v128
	s_nop 0
	v_cndmask_b32_e64 v129, v129, v130, s[0:1]
	v_mul_f32_e32 v130, 0x4b800000, v128
	v_cndmask_b32_e32 v128, v128, v130, vcc
	v_rsq_f32_e32 v129, v129
	v_rsq_f32_e32 v128, v128
	s_nop 0
	v_pk_mul_f32 v[130:131], v[128:129], s[24:25] op_sel_hi:[1,0]
	s_nop 0
	v_cndmask_b32_e32 v175, v128, v130, vcc
	v_cndmask_b32_e64 v174, v129, v131, s[0:1]
	v_lshlrev_b64 v[128:129], 6, v[156:157]
	v_lshl_add_u64 v[140:141], s[20:21], 0, v[128:129]
	global_load_dwordx4 v[128:131], v[140:141], off offset:32
	global_load_dwordx4 v[132:135], v[140:141], off offset:48
	global_load_dwordx4 v[136:139], v[140:141], off
	s_nop 0
	global_load_dwordx4 v[140:143], v[140:141], off offset:16
	s_waitcnt vmcnt(0)
	v_pk_add_f32 v[128:129], v[128:129], v[132:133]
	v_pk_add_f32 v[130:131], v[130:131], v[134:135]
	v_pk_add_f32 v[136:137], v[136:137], v[140:141]
	v_pk_add_f32 v[138:139], v[138:139], v[142:143]
	v_pk_add_f32 v[202:203], v[136:137], v[128:129]
	v_lshlrev_b64 v[128:129], 6, v[154:155]
	v_lshl_add_u64 v[140:141], s[20:21], 0, v[128:129]
	v_pk_add_f32 v[200:201], v[138:139], v[130:131]
	global_load_dwordx4 v[128:131], v[140:141], off offset:32
	global_load_dwordx4 v[132:135], v[140:141], off offset:48
	global_load_dwordx4 v[136:139], v[140:141], off
	s_nop 0
	global_load_dwordx4 v[140:143], v[140:141], off offset:16
	s_waitcnt vmcnt(0)
	v_pk_add_f32 v[128:129], v[128:129], v[132:133]
	v_pk_add_f32 v[130:131], v[130:131], v[134:135]
	v_pk_add_f32 v[136:137], v[136:137], v[140:141]
	v_pk_add_f32 v[138:139], v[138:139], v[142:143]
	v_pk_add_f32 v[128:129], v[136:137], v[128:129]
	v_pk_add_f32 v[130:131], v[138:139], v[130:131]
	v_mov_b32_e32 v132, v128
	v_mov_b32_e32 v133, v202
	v_mov_b32_e32 v202, v129
	v_pk_add_f32 v[128:129], v[132:133], v[202:203]
	v_mov_b32_e32 v132, v130
	v_mov_b32_e32 v133, v200
	v_pk_add_f32 v[128:129], v[132:133], v[128:129]
	v_mov_b32_e32 v200, v131
	v_pk_add_f32 v[128:129], v[200:201], v[128:129]
	s_nop 0
	v_pk_fma_f32 v[128:129], v[128:129], s[2:3], v[198:199] op_sel_hi:[1,0,0]
	s_nop 0
	v_mul_f32_e32 v130, 0x4b800000, v129
	v_cmp_gt_f32_e64 s[0:1], s23, v129
	v_cmp_gt_f32_e32 vcc, s23, v128
	s_nop 0
	v_cndmask_b32_e64 v129, v129, v130, s[0:1]
	v_rsq_f32_e32 v131, v129
	v_mul_f32_e32 v129, 0x4b800000, v128
	v_cndmask_b32_e32 v128, v128, v129, vcc
	v_rsq_f32_e32 v130, v128
	s_nop 0
	v_pk_mul_f32 v[132:133], v[130:131], s[24:25] op_sel_hi:[1,0]
	s_nop 0
	v_cndmask_b32_e32 v129, v130, v132, vcc
	v_cndmask_b32_e64 v128, v131, v133, s[0:1]
	s_mov_b64 s[0:1], 0

.LBB0_170:
	s_add_u32 s20, s48, 0xfffc0080
	s_addc_u32 s21, s49, -1
	s_add_i32 s60, 0, 0x10000
	v_add_u32_e32 v140, s60, v232
	ds_read_b128 v[128:131], v140
	ds_read_b128 v[132:135], v140 offset:1024
	ds_read_b128 v[136:139], v140 offset:2048
	ds_read_b128 v[140:143], v140 offset:3072
	s_cmp_eq_u32 s57, 12
	s_cselect_b32 s51, s43, s21
	s_cselect_b32 s50, s24, s20
	s_cselect_b32 s29, s1, vcc_hi
	s_cselect_b32 s28, s25, vcc_lo
	s_add_i32 m0, s55, 0xc000
	ds_read_b128 v[144:147], v234
	ds_read_b128 v[148:151], v234 offset:1024
	ds_read_b128 v[152:155], v234 offset:2048
	ds_read_b128 v[156:159], v234 offset:3072
	ds_read_b128 v[160:163], v234 offset:4096
	ds_read_b128 v[164:167], v234 offset:5120
	ds_read_b128 v[168:171], v234 offset:6144
	ds_read_b128 v[172:175], v234 offset:7168
	global_load_lds_dwordx4 v204, s[48:49]
	s_add_i32 m0, s55, 0xe000
	s_nop 0
	global_load_lds_dwordx4 v206, s[48:49]
	s_waitcnt lgkmcnt(8)
	s_barrier
	s_waitcnt lgkmcnt(0)
	v_mfma_f32_16x16x32_bf16 v[124:127], v[128:131], v[144:147], v[124:127]
	v_mfma_f32_16x16x32_bf16 v[120:123], v[136:139], v[144:147], v[120:123]
	v_mfma_f32_16x16x32_bf16 v[108:111], v[128:131], v[152:155], v[108:111]
	v_mfma_f32_16x16x32_bf16 v[104:107], v[136:139], v[152:155], v[104:107]
	v_mfma_f32_16x16x32_bf16 v[92:95], v[128:131], v[160:163], v[92:95]
	v_mfma_f32_16x16x32_bf16 v[88:91], v[136:139], v[160:163], v[88:91]
	v_mfma_f32_16x16x32_bf16 v[76:79], v[128:131], v[168:171], v[76:79]
	v_mfma_f32_16x16x32_bf16 v[72:75], v[136:139], v[168:171], v[72:75]
	v_mfma_f32_16x16x32_bf16 v[124:127], v[132:135], v[148:151], v[124:127]
	v_mfma_f32_16x16x32_bf16 v[120:123], v[140:143], v[148:151], v[120:123]
	v_mfma_f32_16x16x32_bf16 v[108:111], v[132:135], v[156:159], v[108:111]
	v_mfma_f32_16x16x32_bf16 v[104:107], v[140:143], v[156:159], v[104:107]
	v_mfma_f32_16x16x32_bf16 v[92:95], v[132:135], v[164:167], v[92:95]
	v_mfma_f32_16x16x32_bf16 v[88:91], v[140:143], v[164:167], v[88:91]
	v_mfma_f32_16x16x32_bf16 v[76:79], v[132:135], v[172:175], v[76:79]
	v_mfma_f32_16x16x32_bf16 v[72:75], v[140:143], v[172:175], v[72:75]
	s_barrier
	s_add_i32 s61, 0, 0x14000
	v_add_u32_e32 v184, s61, v232
	s_add_i32 s20, s60, s54
	ds_read_b128 v[208:211], v184
	ds_read_b128 v[212:215], v184 offset:1024
	ds_read_b128 v[216:219], v184 offset:2048
	ds_read_b128 v[236:239], v184 offset:3072
	s_add_u32 s72, s28, s52
	s_addc_u32 s73, s29, s53
	s_mov_b32 m0, s20
	s_nop 0
	global_load_lds_dwordx4 v176, s[28:29]
	s_add_i32 m0, s20, 0x2000
	s_nop 0
	global_load_lds_dwordx4 v198, s[28:29]
	s_barrier
	s_waitcnt lgkmcnt(0)
	v_mfma_f32_16x16x32_bf16 v[116:119], v[208:211], v[144:147], v[116:119]
	v_mfma_f32_16x16x32_bf16 v[112:115], v[216:219], v[144:147], v[112:115]
	v_mfma_f32_16x16x32_bf16 v[100:103], v[208:211], v[152:155], v[100:103]
	v_mfma_f32_16x16x32_bf16 v[96:99], v[216:219], v[152:155], v[96:99]
	v_mfma_f32_16x16x32_bf16 v[84:87], v[208:211], v[160:163], v[84:87]
	v_mfma_f32_16x16x32_bf16 v[80:83], v[216:219], v[160:163], v[80:83]
	v_mfma_f32_16x16x32_bf16 v[68:71], v[208:211], v[168:171], v[68:71]
	v_mfma_f32_16x16x32_bf16 v[64:67], v[216:219], v[168:171], v[64:67]
	v_mfma_f32_16x16x32_bf16 v[116:119], v[212:215], v[148:151], v[116:119]
	v_mfma_f32_16x16x32_bf16 v[112:115], v[236:239], v[148:151], v[112:115]
	v_mfma_f32_16x16x32_bf16 v[100:103], v[212:215], v[156:159], v[100:103]
	v_mfma_f32_16x16x32_bf16 v[96:99], v[236:239], v[156:159], v[96:99]
	v_mfma_f32_16x16x32_bf16 v[84:87], v[212:215], v[164:167], v[84:87]
	v_mfma_f32_16x16x32_bf16 v[80:83], v[236:239], v[164:167], v[80:83]
	v_mfma_f32_16x16x32_bf16 v[68:71], v[212:215], v[172:175], v[68:71]
	v_mfma_f32_16x16x32_bf16 v[64:67], v[236:239], v[172:175], v[64:67]
	s_mov_b32 m0, s55
	s_add_u32 s70, s50, s52
	s_addc_u32 s71, s51, s53
	s_barrier
	ds_read_b128 v[144:147], v234 offset:16384
	ds_read_b128 v[148:151], v234 offset:17408
	ds_read_b128 v[152:155], v234 offset:18432
	ds_read_b128 v[156:159], v234 offset:19456
	ds_read_b128 v[160:163], v234 offset:20480
	ds_read_b128 v[164:167], v234 offset:21504
	ds_read_b128 v[168:171], v234 offset:22528
	ds_read_b128 v[172:175], v234 offset:23552
	global_load_lds_dwordx4 v202, s[50:51]
	s_mov_b32 m0, s56
	s_nop 0
	global_load_lds_dwordx4 v200, s[50:51]
	s_barrier
	s_waitcnt lgkmcnt(0)
	v_mfma_f32_16x16x32_bf16 v[60:63], v[128:131], v[144:147], v[60:63]
	v_mfma_f32_16x16x32_bf16 v[56:59], v[136:139], v[144:147], v[56:59]
	v_mfma_f32_16x16x32_bf16 v[44:47], v[128:131], v[152:155], v[44:47]
	v_mfma_f32_16x16x32_bf16 v[40:43], v[136:139], v[152:155], v[40:43]
	v_mfma_f32_16x16x32_bf16 v[28:31], v[128:131], v[160:163], v[28:31]
	v_mfma_f32_16x16x32_bf16 v[24:27], v[136:139], v[160:163], v[24:27]
	v_mfma_f32_16x16x32_bf16 v[12:15], v[128:131], v[168:171], v[12:15]
	v_mfma_f32_16x16x32_bf16 v[8:11], v[136:139], v[168:171], v[8:11]
	v_mfma_f32_16x16x32_bf16 v[60:63], v[132:135], v[148:151], v[60:63]
	v_mfma_f32_16x16x32_bf16 v[56:59], v[140:143], v[148:151], v[56:59]
	v_mfma_f32_16x16x32_bf16 v[44:47], v[132:135], v[156:159], v[44:47]
	v_mfma_f32_16x16x32_bf16 v[40:43], v[140:143], v[156:159], v[40:43]
	v_mfma_f32_16x16x32_bf16 v[28:31], v[132:135], v[164:167], v[28:31]
	v_mfma_f32_16x16x32_bf16 v[24:27], v[140:143], v[164:167], v[24:27]
	v_mfma_f32_16x16x32_bf16 v[12:15], v[132:135], v[172:175], v[12:15]
	v_mfma_f32_16x16x32_bf16 v[8:11], v[140:143], v[172:175], v[8:11]
	s_barrier
	s_add_u32 s20, s28, 0x40000
	s_addc_u32 s21, s29, 0
	s_add_i32 s60, s61, s54
	s_mov_b32 m0, s60
	s_nop 0
	global_load_lds_dwordx4 v176, s[20:21]
	s_add_i32 m0, s60, 0x2000
	s_nop 0
	global_load_lds_dwordx4 v198, s[20:21]
	s_waitcnt vmcnt(6)
	s_barrier
	v_mfma_f32_16x16x32_bf16 v[52:55], v[208:211], v[144:147], v[52:55]
	v_mfma_f32_16x16x32_bf16 v[48:51], v[216:219], v[144:147], v[48:51]
	v_mfma_f32_16x16x32_bf16 v[36:39], v[208:211], v[152:155], v[36:39]
	v_mfma_f32_16x16x32_bf16 v[32:35], v[216:219], v[152:155], v[32:35]
	v_mfma_f32_16x16x32_bf16 v[20:23], v[208:211], v[160:163], v[20:23]
	v_mfma_f32_16x16x32_bf16 v[16:19], v[216:219], v[160:163], v[16:19]
	v_mfma_f32_16x16x32_bf16 v[4:7], v[208:211], v[168:171], v[4:7]
	v_mfma_f32_16x16x32_bf16 v[0:3], v[216:219], v[168:171], v[0:3]
	v_mfma_f32_16x16x32_bf16 v[52:55], v[212:215], v[148:151], v[52:55]
	v_mfma_f32_16x16x32_bf16 v[48:51], v[236:239], v[148:151], v[48:51]
	v_mfma_f32_16x16x32_bf16 v[36:39], v[212:215], v[156:159], v[36:39]
	v_mfma_f32_16x16x32_bf16 v[32:35], v[236:239], v[156:159], v[32:35]
	v_mfma_f32_16x16x32_bf16 v[20:23], v[212:215], v[164:167], v[20:23]
	v_mfma_f32_16x16x32_bf16 v[16:19], v[236:239], v[164:167], v[16:19]
	v_mfma_f32_16x16x32_bf16 v[4:7], v[212:215], v[172:175], v[4:7]
	v_mfma_f32_16x16x32_bf16 v[0:3], v[236:239], v[172:175], v[0:3]
	s_add_i32 s60, 0, 0x18000
	v_add_u32_e32 v140, s60, v232
	s_barrier
	ds_read_b128 v[128:131], v140
	ds_read_b128 v[132:135], v140 offset:1024
	ds_read_b128 v[136:139], v140 offset:2048
	ds_read_b128 v[140:143], v140 offset:3072
	s_add_u32 s20, s50, 0x40000
	s_addc_u32 s21, s51, 0
	s_mov_b32 m0, s7
	ds_read_b128 v[144:147], v234 offset:32768
	ds_read_b128 v[148:151], v234 offset:33792
	ds_read_b128 v[152:155], v234 offset:34816
	ds_read_b128 v[156:159], v234 offset:35840
	ds_read_b128 v[160:163], v234 offset:36864
	ds_read_b128 v[164:167], v234 offset:37888
	ds_read_b128 v[168:171], v234 offset:38912
	ds_read_b128 v[172:175], v234 offset:39936
	global_load_lds_dwordx4 v202, s[20:21]
	s_mov_b32 m0, s15
	s_nop 0
	global_load_lds_dwordx4 v200, s[20:21]
	s_waitcnt lgkmcnt(8)
	s_barrier
	s_waitcnt lgkmcnt(0)
	v_mfma_f32_16x16x32_bf16 v[124:127], v[128:131], v[144:147], v[124:127]
	v_mfma_f32_16x16x32_bf16 v[120:123], v[136:139], v[144:147], v[120:123]
	v_mfma_f32_16x16x32_bf16 v[108:111], v[128:131], v[152:155], v[108:111]
	v_mfma_f32_16x16x32_bf16 v[104:107], v[136:139], v[152:155], v[104:107]
	v_mfma_f32_16x16x32_bf16 v[92:95], v[128:131], v[160:163], v[92:95]
	v_mfma_f32_16x16x32_bf16 v[88:91], v[136:139], v[160:163], v[88:91]
	v_mfma_f32_16x16x32_bf16 v[76:79], v[128:131], v[168:171], v[76:79]
	v_mfma_f32_16x16x32_bf16 v[72:75], v[136:139], v[168:171], v[72:75]
	v_mfma_f32_16x16x32_bf16 v[124:127], v[132:135], v[148:151], v[124:127]
	v_mfma_f32_16x16x32_bf16 v[120:123], v[140:143], v[148:151], v[120:123]
	v_mfma_f32_16x16x32_bf16 v[108:111], v[132:135], v[156:159], v[108:111]
	v_mfma_f32_16x16x32_bf16 v[104:107], v[140:143], v[156:159], v[104:107]
	v_mfma_f32_16x16x32_bf16 v[92:95], v[132:135], v[164:167], v[92:95]
	v_mfma_f32_16x16x32_bf16 v[88:91], v[140:143], v[164:167], v[88:91]
	v_mfma_f32_16x16x32_bf16 v[76:79], v[132:135], v[172:175], v[76:79]
	v_mfma_f32_16x16x32_bf16 v[72:75], v[140:143], v[172:175], v[72:75]
	s_barrier
	s_add_i32 s50, 0, 0x1c000
	s_add_i32 s20, s60, s54
	v_add_u32_e32 v235, s50, v232
	s_mov_b32 m0, s20
	ds_read_b128 v[208:211], v235
	ds_read_b128 v[212:215], v235 offset:1024
	ds_read_b128 v[216:219], v235 offset:2048
	ds_read_b128 v[236:239], v235 offset:3072
	global_load_lds_dwordx4 v176, s[72:73]
	s_add_i32 m0, s20, 0x2000
	s_nop 0
	global_load_lds_dwordx4 v198, s[72:73]
	s_barrier
	s_waitcnt lgkmcnt(0)
	v_mfma_f32_16x16x32_bf16 v[116:119], v[208:211], v[144:147], v[116:119]
	v_mfma_f32_16x16x32_bf16 v[112:115], v[216:219], v[144:147], v[112:115]
	v_mfma_f32_16x16x32_bf16 v[100:103], v[208:211], v[152:155], v[100:103]
	v_mfma_f32_16x16x32_bf16 v[96:99], v[216:219], v[152:155], v[96:99]
	v_mfma_f32_16x16x32_bf16 v[84:87], v[208:211], v[160:163], v[84:87]
	v_mfma_f32_16x16x32_bf16 v[80:83], v[216:219], v[160:163], v[80:83]
	v_mfma_f32_16x16x32_bf16 v[68:71], v[208:211], v[168:171], v[68:71]
	v_mfma_f32_16x16x32_bf16 v[64:67], v[216:219], v[168:171], v[64:67]
	v_mfma_f32_16x16x32_bf16 v[116:119], v[212:215], v[148:151], v[116:119]
	v_mfma_f32_16x16x32_bf16 v[112:115], v[236:239], v[148:151], v[112:115]
	v_mfma_f32_16x16x32_bf16 v[100:103], v[212:215], v[156:159], v[100:103]
	v_mfma_f32_16x16x32_bf16 v[96:99], v[236:239], v[156:159], v[96:99]
	v_mfma_f32_16x16x32_bf16 v[84:87], v[212:215], v[164:167], v[84:87]
	v_mfma_f32_16x16x32_bf16 v[80:83], v[236:239], v[164:167], v[80:83]
	v_mfma_f32_16x16x32_bf16 v[68:71], v[212:215], v[172:175], v[68:71]
	v_mfma_f32_16x16x32_bf16 v[64:67], v[236:239], v[172:175], v[64:67]
	s_mov_b32 m0, s3
	s_barrier
	ds_read_b128 v[144:147], v234 offset:49152
	ds_read_b128 v[148:151], v234 offset:50176
	ds_read_b128 v[152:155], v234 offset:51200
	ds_read_b128 v[156:159], v234 offset:52224
	ds_read_b128 v[160:163], v234 offset:53248
	ds_read_b128 v[164:167], v234 offset:54272
	ds_read_b128 v[168:171], v234 offset:55296
	ds_read_b128 v[172:175], v234 offset:56320
	global_load_lds_dwordx4 v202, s[70:71]
	s_mov_b32 m0, s6
	s_nop 0
	global_load_lds_dwordx4 v200, s[70:71]
	s_barrier
	s_waitcnt lgkmcnt(0)
	v_mfma_f32_16x16x32_bf16 v[60:63], v[128:131], v[144:147], v[60:63]
	v_mfma_f32_16x16x32_bf16 v[56:59], v[136:139], v[144:147], v[56:59]
	v_mfma_f32_16x16x32_bf16 v[44:47], v[128:131], v[152:155], v[44:47]
	v_mfma_f32_16x16x32_bf16 v[40:43], v[136:139], v[152:155], v[40:43]
	v_mfma_f32_16x16x32_bf16 v[28:31], v[128:131], v[160:163], v[28:31]
	v_mfma_f32_16x16x32_bf16 v[24:27], v[136:139], v[160:163], v[24:27]
	v_mfma_f32_16x16x32_bf16 v[12:15], v[128:131], v[168:171], v[12:15]
	v_mfma_f32_16x16x32_bf16 v[8:11], v[136:139], v[168:171], v[8:11]
	v_mfma_f32_16x16x32_bf16 v[60:63], v[132:135], v[148:151], v[60:63]
	v_mfma_f32_16x16x32_bf16 v[56:59], v[140:143], v[148:151], v[56:59]
	v_mfma_f32_16x16x32_bf16 v[44:47], v[132:135], v[156:159], v[44:47]
	v_mfma_f32_16x16x32_bf16 v[40:43], v[140:143], v[156:159], v[40:43]
	v_mfma_f32_16x16x32_bf16 v[28:31], v[132:135], v[164:167], v[28:31]
	v_mfma_f32_16x16x32_bf16 v[24:27], v[140:143], v[164:167], v[24:27]
	v_mfma_f32_16x16x32_bf16 v[12:15], v[132:135], v[172:175], v[12:15]
	v_mfma_f32_16x16x32_bf16 v[8:11], v[140:143], v[172:175], v[8:11]
	s_barrier
	s_add_u32 s20, s28, 0x40080
	s_addc_u32 s21, s29, 0
	s_add_i32 s28, s50, s54
	s_mov_b32 m0, s28
	s_nop 0
	global_load_lds_dwordx4 v176, s[20:21]
	s_add_i32 m0, s28, 0x2000
	s_nop 0
	global_load_lds_dwordx4 v198, s[20:21]
	s_waitcnt vmcnt(6)
	s_barrier
	v_mfma_f32_16x16x32_bf16 v[52:55], v[208:211], v[144:147], v[52:55]
	v_mfma_f32_16x16x32_bf16 v[48:51], v[216:219], v[144:147], v[48:51]
	v_mfma_f32_16x16x32_bf16 v[36:39], v[208:211], v[152:155], v[36:39]
	v_mfma_f32_16x16x32_bf16 v[32:35], v[216:219], v[152:155], v[32:35]
	v_mfma_f32_16x16x32_bf16 v[20:23], v[208:211], v[160:163], v[20:23]
	v_mfma_f32_16x16x32_bf16 v[16:19], v[216:219], v[160:163], v[16:19]
	v_mfma_f32_16x16x32_bf16 v[4:7], v[208:211], v[168:171], v[4:7]
	v_mfma_f32_16x16x32_bf16 v[0:3], v[216:219], v[168:171], v[0:3]
	v_mfma_f32_16x16x32_bf16 v[52:55], v[212:215], v[148:151], v[52:55]
	v_mfma_f32_16x16x32_bf16 v[48:51], v[236:239], v[148:151], v[48:51]
	v_mfma_f32_16x16x32_bf16 v[36:39], v[212:215], v[156:159], v[36:39]
	v_mfma_f32_16x16x32_bf16 v[32:35], v[236:239], v[156:159], v[32:35]
	v_mfma_f32_16x16x32_bf16 v[20:23], v[212:215], v[164:167], v[20:23]
	v_mfma_f32_16x16x32_bf16 v[16:19], v[236:239], v[164:167], v[16:19]
	v_mfma_f32_16x16x32_bf16 v[4:7], v[212:215], v[172:175], v[4:7]
	v_mfma_f32_16x16x32_bf16 v[0:3], v[236:239], v[172:175], v[0:3]
	s_add_i32 s57, s57, 2
	s_add_u32 s48, s48, 0x100
	s_addc_u32 s49, s49, 0
	s_add_u32 vcc_lo, vcc_lo, 0x100
	s_addc_u32 vcc_hi, vcc_hi, 0
	s_cmp_gt_u32 s57, 13
	s_barrier
	s_cbranch_scc0 .LBB0_170
	v_lshl_add_u32 v210, s2, 8, v231
	v_lshl_or_b32 v208, s34, 8, v233
	v_readlane_b32 s60, v252, 10
	v_ashrrev_i32_e32 v209, 31, v208
	v_readlane_b32 s61, v252, 11
	v_ashrrev_i32_e32 v211, 31, v210
	v_lshlrev_b64 v[128:129], 12, v[210:211]
	v_lshl_add_u64 v[212:213], v[208:209], 2, s[60:61]
	v_lshl_add_u64 v[128:129], v[212:213], 0, v[128:129]
	global_load_dwordx4 v[236:239], v[128:129], off offset:16
	global_load_dwordx4 v[240:243], v[128:129], off
	global_load_dwordx4 v[244:247], v[128:129], off offset:528
	global_load_dwordx4 v[248:251], v[128:129], off offset:512
	v_or_b32_e32 v218, 16, v210
	v_ashrrev_i32_e32 v219, 31, v218
	v_lshlrev_b64 v[128:129], 12, v[218:219]
	v_or_b32_e32 v216, 32, v210
	v_lshl_add_u64 v[128:129], v[212:213], 0, v[128:129]
	v_ashrrev_i32_e32 v217, 31, v216
	global_load_dwordx4 v[168:171], v[128:129], off offset:16
	global_load_dwordx4 v[172:175], v[128:129], off
	global_load_dwordx4 v[160:163], v[128:129], off offset:528
	global_load_dwordx4 v[164:167], v[128:129], off offset:512
	v_lshlrev_b64 v[128:129], 12, v[216:217]
	v_or_b32_e32 v214, 48, v210
	v_lshl_add_u64 v[128:129], v[212:213], 0, v[128:129]
	v_ashrrev_i32_e32 v215, 31, v214
	global_load_dwordx4 v[152:155], v[128:129], off offset:16
	global_load_dwordx4 v[156:159], v[128:129], off
	global_load_dwordx4 v[136:139], v[128:129], off offset:528
	global_load_dwordx4 v[144:147], v[128:129], off offset:512
	v_lshlrev_b64 v[128:129], 12, v[214:215]
	v_lshl_add_u64 v[132:133], v[212:213], 0, v[128:129]
	global_load_dwordx4 v[140:143], v[132:133], off offset:16
	global_load_dwordx4 v[148:151], v[132:133], off
	global_load_dwordx4 v[128:131], v[132:133], off offset:528
	s_nop 0
	global_load_dwordx4 v[132:135], v[132:133], off offset:512
	v_readlane_b32 s68, v252, 18
	v_readlane_b32 s69, v252, 19
	v_readlane_b32 s68, v255, 14
	v_readlane_b32 s69, v255, 15
	s_lshl_b32 s48, s34, 2
	s_ashr_i32 s49, s48, 31
	v_readlane_b32 s62, v252, 12
	v_readlane_b32 s63, v252, 13
	v_readlane_b32 s64, v252, 14
	v_readlane_b32 s65, v252, 15
	v_readlane_b32 s66, v252, 16
	v_readlane_b32 s67, v252, 17
	v_readlane_b32 s70, v252, 20
	v_readlane_b32 s71, v252, 21
	v_readlane_b32 s72, v252, 22
	v_readlane_b32 s73, v252, 23
	v_readlane_b32 s74, v252, 24
	v_readlane_b32 s75, v252, 25
	s_waitcnt vmcnt(0)
	v_pk_add_f32 v[184:185], v[122:123], v[238:239]
	v_pk_add_f32 v[122:123], v[120:121], v[236:237]
	v_pk_add_f32 v[124:125], v[124:125], v[240:241]
	v_mul_f32_e32 v120, v122, v122
	v_mul_f32_e32 v121, v123, v123
	v_fmac_f32_e32 v120, v124, v124
	v_fmac_f32_e32 v121, v125, v125
	v_pk_add_f32 v[126:127], v[126:127], v[242:243]
	v_add_f32_e32 v120, v120, v121
	v_mul_f32_e32 v121, v184, v184
	v_fmac_f32_e32 v121, v126, v126
	v_add_f32_e32 v120, v121, v120
	v_mul_f32_e32 v121, v185, v185
	v_fmac_f32_e32 v121, v127, v127
	v_add_f32_e32 v192, v121, v120
	v_cvt_pk_bf16_f32 v120, v124, v125
	v_lshlrev_b64 v[124:125], 11, v[210:211]
	v_lshl_add_u64 v[124:125], s[68:69], 0, v[124:125]
	v_cvt_pk_bf16_f32 v121, v126, v127
	v_lshl_add_u64 v[124:125], v[208:209], 1, v[124:125]
	v_cvt_pk_bf16_f32 v122, v122, v123
	v_cvt_pk_bf16_f32 v123, v184, v185
	global_store_dwordx4 v[124:125], v[120:123], off
	v_pk_add_f32 v[116:117], v[116:117], v[248:249]
	v_pk_add_f32 v[118:119], v[118:119], v[250:251]
	v_pk_add_f32 v[120:121], v[114:115], v[246:247]
	v_pk_add_f32 v[114:115], v[112:113], v[244:245]
	s_nop 0
	v_mul_f32_e32 v112, v114, v114
	v_fmac_f32_e32 v112, v116, v116
	v_mul_f32_e32 v113, v115, v115
	v_add_f32_e32 v112, v112, v192
	v_fmac_f32_e32 v113, v117, v117
	v_add_f32_e32 v112, v113, v112
	v_mul_f32_e32 v113, v120, v120
	v_fmac_f32_e32 v113, v118, v118
	v_add_f32_e32 v112, v113, v112
	v_mul_f32_e32 v113, v121, v121
	v_fmac_f32_e32 v113, v119, v119
	v_add_f32_e32 v122, v113, v112
	v_cvt_pk_bf16_f32 v112, v116, v117
	v_cvt_pk_bf16_f32 v113, v118, v119
	v_cvt_pk_bf16_f32 v114, v114, v115
	v_cvt_pk_bf16_f32 v115, v120, v121
	global_store_dwordx4 v[124:125], v[112:115], off offset:256
	s_nop 1
	v_and_b32_e32 v113, 64, v225
	v_xor_b32_e32 v112, 16, v225
	v_add_u32_e32 v113, 64, v113
	v_cmp_lt_i32_e32 vcc, v112, v113
	v_xor_b32_e32 v114, 32, v225
	s_nop 0
	v_cndmask_b32_e32 v112, v225, v112, vcc
	v_lshlrev_b32_e32 v235, 2, v112
	ds_bpermute_b32 v112, v235, v122
	v_cmp_lt_i32_e32 vcc, v114, v113
	s_waitcnt lgkmcnt(0)
	v_add_f32_e32 v112, v122, v112
	v_cndmask_b32_e32 v113, v225, v114, vcc
	v_lshlrev_b32_e32 v236, 2, v113
	ds_bpermute_b32 v113, v236, v112
	s_and_saveexec_b64 s[28:29], s[38:39]
	s_cbranch_execz .LBB0_173
	v_readlane_b32 s20, v253, 31
	v_lshlrev_b64 v[114:115], 6, v[210:211]
	v_readlane_b32 s21, v253, 32
	s_lshl_b32 s34, s58, 2
	s_waitcnt lgkmcnt(0)
	v_add_f32_e32 v112, v112, v113
	v_lshl_add_u64 v[114:115], s[20:21], 0, v[114:115]
	v_lshl_add_u64 v[114:115], s[48:49], 2, v[114:115]
	v_lshl_add_u64 v[114:115], v[114:115], 0, s[34:35]
	global_store_dword v[114:115], v112, off

.LBB0_292:
	s_add_u32 s20, s46, 0xfffc0080
	s_addc_u32 s21, s47, -1
	s_add_i32 s60, 0, 0x10000
	v_add_u32_e32 v138, s60, v141
	ds_read_b128 v[144:147], v138
	ds_read_b128 v[148:151], v138 offset:1024
	ds_read_b128 v[152:155], v138 offset:2048
	ds_read_b128 v[156:159], v138 offset:3072
	s_cmp_eq_u32 vcc_lo, 12
	s_cselect_b32 s49, s41, s21
	s_cselect_b32 s48, s24, s20
	s_cselect_b32 s29, s1, s59
	s_cselect_b32 s28, s25, s58
	s_add_i32 m0, s7, 0xc000
	ds_read_b128 v[160:163], v143
	ds_read_b128 v[164:167], v143 offset:1024
	ds_read_b128 v[168:171], v143 offset:2048
	ds_read_b128 v[172:175], v143 offset:3072
	ds_read_b128 v[198:201], v143 offset:4096
	ds_read_b128 v[202:205], v143 offset:5120
	ds_read_b128 v[206:209], v143 offset:6144
	ds_read_b128 v[210:213], v143 offset:7168
	global_load_lds_dwordx4 v134, s[46:47]
	s_add_i32 m0, s7, 0xe000
	s_nop 0
	global_load_lds_dwordx4 v136, s[46:47]
	s_waitcnt lgkmcnt(8)
	s_barrier
	s_waitcnt lgkmcnt(0)
	v_mfma_f32_16x16x32_bf16 v[124:127], v[144:147], v[160:163], v[124:127]
	v_mfma_f32_16x16x32_bf16 v[120:123], v[152:155], v[160:163], v[120:123]
	v_mfma_f32_16x16x32_bf16 v[116:119], v[144:147], v[168:171], v[116:119]
	v_mfma_f32_16x16x32_bf16 v[108:111], v[152:155], v[168:171], v[108:111]
	v_mfma_f32_16x16x32_bf16 v[100:103], v[144:147], v[198:201], v[100:103]
	v_mfma_f32_16x16x32_bf16 v[92:95], v[152:155], v[198:201], v[92:95]
	v_mfma_f32_16x16x32_bf16 v[80:83], v[144:147], v[206:209], v[80:83]
	v_mfma_f32_16x16x32_bf16 v[72:75], v[152:155], v[206:209], v[72:75]
	v_mfma_f32_16x16x32_bf16 v[124:127], v[148:151], v[164:167], v[124:127]
	v_mfma_f32_16x16x32_bf16 v[120:123], v[156:159], v[164:167], v[120:123]
	v_mfma_f32_16x16x32_bf16 v[116:119], v[148:151], v[172:175], v[116:119]
	v_mfma_f32_16x16x32_bf16 v[108:111], v[156:159], v[172:175], v[108:111]
	v_mfma_f32_16x16x32_bf16 v[100:103], v[148:151], v[202:205], v[100:103]
	v_mfma_f32_16x16x32_bf16 v[92:95], v[156:159], v[202:205], v[92:95]
	v_mfma_f32_16x16x32_bf16 v[80:83], v[148:151], v[210:213], v[80:83]
	v_mfma_f32_16x16x32_bf16 v[72:75], v[156:159], v[210:213], v[72:75]
	s_barrier
	s_add_i32 s61, 0, 0x14000
	v_add_u32_e32 v138, s61, v141
	s_add_i32 s20, s60, s6
	ds_read_b128 v[214:217], v138
	ds_read_b128 v[232:235], v138 offset:1024
	ds_read_b128 v[236:239], v138 offset:2048
	ds_read_b128 v[240:243], v138 offset:3072
	s_add_u32 s72, s28, s52
	s_addc_u32 s73, s29, s53
	s_mov_b32 m0, s20
	s_nop 0
	global_load_lds_dwordx4 v176, s[28:29]
	s_add_i32 m0, s20, 0x2000
	s_nop 0
	global_load_lds_dwordx4 v128, s[28:29]
	s_barrier
	s_waitcnt lgkmcnt(0)
	v_mfma_f32_16x16x32_bf16 v[112:115], v[214:217], v[160:163], v[112:115]
	v_mfma_f32_16x16x32_bf16 v[104:107], v[236:239], v[160:163], v[104:107]
	v_mfma_f32_16x16x32_bf16 v[96:99], v[214:217], v[168:171], v[96:99]
	v_mfma_f32_16x16x32_bf16 v[88:91], v[236:239], v[168:171], v[88:91]
	v_mfma_f32_16x16x32_bf16 v[84:87], v[214:217], v[198:201], v[84:87]
	v_mfma_f32_16x16x32_bf16 v[76:79], v[236:239], v[198:201], v[76:79]
	v_mfma_f32_16x16x32_bf16 v[68:71], v[214:217], v[206:209], v[68:71]
	v_mfma_f32_16x16x32_bf16 v[64:67], v[236:239], v[206:209], v[64:67]
	v_mfma_f32_16x16x32_bf16 v[112:115], v[232:235], v[164:167], v[112:115]
	v_mfma_f32_16x16x32_bf16 v[104:107], v[240:243], v[164:167], v[104:107]
	v_mfma_f32_16x16x32_bf16 v[96:99], v[232:235], v[172:175], v[96:99]
	v_mfma_f32_16x16x32_bf16 v[88:91], v[240:243], v[172:175], v[88:91]
	v_mfma_f32_16x16x32_bf16 v[84:87], v[232:235], v[202:205], v[84:87]
	v_mfma_f32_16x16x32_bf16 v[76:79], v[240:243], v[202:205], v[76:79]
	v_mfma_f32_16x16x32_bf16 v[68:71], v[232:235], v[210:213], v[68:71]
	v_mfma_f32_16x16x32_bf16 v[64:67], v[240:243], v[210:213], v[64:67]
	s_mov_b32 m0, s7
	s_add_u32 s94, s48, s52
	s_addc_u32 s95, s49, s53
	s_barrier
	ds_read_b128 v[160:163], v143 offset:16384
	ds_read_b128 v[164:167], v143 offset:17408
	ds_read_b128 v[168:171], v143 offset:18432
	ds_read_b128 v[172:175], v143 offset:19456
	ds_read_b128 v[198:201], v143 offset:20480
	ds_read_b128 v[202:205], v143 offset:21504
	ds_read_b128 v[206:209], v143 offset:22528
	ds_read_b128 v[210:213], v143 offset:23552
	global_load_lds_dwordx4 v132, s[48:49]
	s_mov_b32 m0, s9
	s_nop 0
	global_load_lds_dwordx4 v130, s[48:49]
	s_barrier
	s_waitcnt lgkmcnt(0)
	v_mfma_f32_16x16x32_bf16 v[60:63], v[144:147], v[160:163], v[60:63]
	v_mfma_f32_16x16x32_bf16 v[56:59], v[152:155], v[160:163], v[56:59]
	v_mfma_f32_16x16x32_bf16 v[52:55], v[144:147], v[168:171], v[52:55]
	v_mfma_f32_16x16x32_bf16 v[44:47], v[152:155], v[168:171], v[44:47]
	v_mfma_f32_16x16x32_bf16 v[36:39], v[144:147], v[198:201], v[36:39]
	v_mfma_f32_16x16x32_bf16 v[28:31], v[152:155], v[198:201], v[28:31]
	v_mfma_f32_16x16x32_bf16 v[20:23], v[144:147], v[206:209], v[20:23]
	v_mfma_f32_16x16x32_bf16 v[12:15], v[152:155], v[206:209], v[12:15]
	v_mfma_f32_16x16x32_bf16 v[60:63], v[148:151], v[164:167], v[60:63]
	v_mfma_f32_16x16x32_bf16 v[56:59], v[156:159], v[164:167], v[56:59]
	v_mfma_f32_16x16x32_bf16 v[52:55], v[148:151], v[172:175], v[52:55]
	v_mfma_f32_16x16x32_bf16 v[44:47], v[156:159], v[172:175], v[44:47]
	v_mfma_f32_16x16x32_bf16 v[36:39], v[148:151], v[202:205], v[36:39]
	v_mfma_f32_16x16x32_bf16 v[28:31], v[156:159], v[202:205], v[28:31]
	v_mfma_f32_16x16x32_bf16 v[20:23], v[148:151], v[210:213], v[20:23]
	v_mfma_f32_16x16x32_bf16 v[12:15], v[156:159], v[210:213], v[12:15]
	s_barrier
	s_add_u32 s20, s28, 0x40000
	s_addc_u32 s21, s29, 0
	s_add_i32 s60, s61, s6
	s_mov_b32 m0, s60
	s_nop 0
	global_load_lds_dwordx4 v176, s[20:21]
	s_add_i32 m0, s60, 0x2000
	s_nop 0
	global_load_lds_dwordx4 v128, s[20:21]
	s_waitcnt vmcnt(6)
	s_barrier
	v_mfma_f32_16x16x32_bf16 v[48:51], v[214:217], v[160:163], v[48:51]
	v_mfma_f32_16x16x32_bf16 v[40:43], v[236:239], v[160:163], v[40:43]
	v_mfma_f32_16x16x32_bf16 v[32:35], v[214:217], v[168:171], v[32:35]
	v_mfma_f32_16x16x32_bf16 v[24:27], v[236:239], v[168:171], v[24:27]
	v_mfma_f32_16x16x32_bf16 v[16:19], v[214:217], v[198:201], v[16:19]
	v_mfma_f32_16x16x32_bf16 v[8:11], v[236:239], v[198:201], v[8:11]
	v_mfma_f32_16x16x32_bf16 v[4:7], v[214:217], v[206:209], v[4:7]
	v_mfma_f32_16x16x32_bf16 v[0:3], v[236:239], v[206:209], v[0:3]
	v_mfma_f32_16x16x32_bf16 v[48:51], v[232:235], v[164:167], v[48:51]
	v_mfma_f32_16x16x32_bf16 v[40:43], v[240:243], v[164:167], v[40:43]
	v_mfma_f32_16x16x32_bf16 v[32:35], v[232:235], v[172:175], v[32:35]
	v_mfma_f32_16x16x32_bf16 v[24:27], v[240:243], v[172:175], v[24:27]
	v_mfma_f32_16x16x32_bf16 v[16:19], v[232:235], v[202:205], v[16:19]
	v_mfma_f32_16x16x32_bf16 v[8:11], v[240:243], v[202:205], v[8:11]
	v_mfma_f32_16x16x32_bf16 v[4:7], v[232:235], v[210:213], v[4:7]
	v_mfma_f32_16x16x32_bf16 v[0:3], v[240:243], v[210:213], v[0:3]
	s_add_i32 s60, 0, 0x18000
	v_add_u32_e32 v156, s60, v141
	s_barrier
	ds_read_b128 v[144:147], v156
	ds_read_b128 v[148:151], v156 offset:1024
	ds_read_b128 v[152:155], v156 offset:2048
	ds_read_b128 v[156:159], v156 offset:3072
	s_add_u32 s20, s48, 0x40000
	s_addc_u32 s21, s49, 0
	s_mov_b32 m0, s15
	ds_read_b128 v[160:163], v143 offset:32768
	ds_read_b128 v[164:167], v143 offset:33792
	ds_read_b128 v[168:171], v143 offset:34816
	ds_read_b128 v[172:175], v143 offset:35840
	ds_read_b128 v[198:201], v143 offset:36864
	ds_read_b128 v[202:205], v143 offset:37888
	ds_read_b128 v[206:209], v143 offset:38912
	ds_read_b128 v[210:213], v143 offset:39936
	global_load_lds_dwordx4 v132, s[20:21]
	s_mov_b32 m0, s34
	s_nop 0
	global_load_lds_dwordx4 v130, s[20:21]
	s_waitcnt lgkmcnt(8)
	s_barrier
	s_waitcnt lgkmcnt(0)
	v_mfma_f32_16x16x32_bf16 v[124:127], v[144:147], v[160:163], v[124:127]
	v_mfma_f32_16x16x32_bf16 v[120:123], v[152:155], v[160:163], v[120:123]
	v_mfma_f32_16x16x32_bf16 v[116:119], v[144:147], v[168:171], v[116:119]
	v_mfma_f32_16x16x32_bf16 v[108:111], v[152:155], v[168:171], v[108:111]
	v_mfma_f32_16x16x32_bf16 v[100:103], v[144:147], v[198:201], v[100:103]
	v_mfma_f32_16x16x32_bf16 v[92:95], v[152:155], v[198:201], v[92:95]
	v_mfma_f32_16x16x32_bf16 v[80:83], v[144:147], v[206:209], v[80:83]
	v_mfma_f32_16x16x32_bf16 v[72:75], v[152:155], v[206:209], v[72:75]
	v_mfma_f32_16x16x32_bf16 v[124:127], v[148:151], v[164:167], v[124:127]
	v_mfma_f32_16x16x32_bf16 v[120:123], v[156:159], v[164:167], v[120:123]
	v_mfma_f32_16x16x32_bf16 v[116:119], v[148:151], v[172:175], v[116:119]
	v_mfma_f32_16x16x32_bf16 v[108:111], v[156:159], v[172:175], v[108:111]
	v_mfma_f32_16x16x32_bf16 v[100:103], v[148:151], v[202:205], v[100:103]
	v_mfma_f32_16x16x32_bf16 v[92:95], v[156:159], v[202:205], v[92:95]
	v_mfma_f32_16x16x32_bf16 v[80:83], v[148:151], v[210:213], v[80:83]
	v_mfma_f32_16x16x32_bf16 v[72:75], v[156:159], v[210:213], v[72:75]
	s_barrier
	s_add_i32 s48, 0, 0x1c000
	s_add_i32 s20, s60, s6
	v_add_u32_e32 v184, s48, v141
	s_mov_b32 m0, s20
	ds_read_b128 v[214:217], v184
	ds_read_b128 v[232:235], v184 offset:1024
	ds_read_b128 v[236:239], v184 offset:2048
	ds_read_b128 v[240:243], v184 offset:3072
	global_load_lds_dwordx4 v176, s[72:73]
	s_add_i32 m0, s20, 0x2000
	s_nop 0
	global_load_lds_dwordx4 v128, s[72:73]
	s_barrier
	s_waitcnt lgkmcnt(0)
	v_mfma_f32_16x16x32_bf16 v[112:115], v[214:217], v[160:163], v[112:115]
	v_mfma_f32_16x16x32_bf16 v[104:107], v[236:239], v[160:163], v[104:107]
	v_mfma_f32_16x16x32_bf16 v[96:99], v[214:217], v[168:171], v[96:99]
	v_mfma_f32_16x16x32_bf16 v[88:91], v[236:239], v[168:171], v[88:91]
	v_mfma_f32_16x16x32_bf16 v[84:87], v[214:217], v[198:201], v[84:87]
	v_mfma_f32_16x16x32_bf16 v[76:79], v[236:239], v[198:201], v[76:79]
	v_mfma_f32_16x16x32_bf16 v[68:71], v[214:217], v[206:209], v[68:71]
	v_mfma_f32_16x16x32_bf16 v[64:67], v[236:239], v[206:209], v[64:67]
	v_mfma_f32_16x16x32_bf16 v[112:115], v[232:235], v[164:167], v[112:115]
	v_mfma_f32_16x16x32_bf16 v[104:107], v[240:243], v[164:167], v[104:107]
	v_mfma_f32_16x16x32_bf16 v[96:99], v[232:235], v[172:175], v[96:99]
	v_mfma_f32_16x16x32_bf16 v[88:91], v[240:243], v[172:175], v[88:91]
	v_mfma_f32_16x16x32_bf16 v[84:87], v[232:235], v[202:205], v[84:87]
	v_mfma_f32_16x16x32_bf16 v[76:79], v[240:243], v[202:205], v[76:79]
	v_mfma_f32_16x16x32_bf16 v[68:71], v[232:235], v[210:213], v[68:71]
	v_mfma_f32_16x16x32_bf16 v[64:67], v[240:243], v[210:213], v[64:67]
	s_mov_b32 m0, s51
	s_barrier
	ds_read_b128 v[160:163], v143 offset:49152
	ds_read_b128 v[164:167], v143 offset:50176
	ds_read_b128 v[168:171], v143 offset:51200
	ds_read_b128 v[172:175], v143 offset:52224
	ds_read_b128 v[198:201], v143 offset:53248
	ds_read_b128 v[202:205], v143 offset:54272
	ds_read_b128 v[206:209], v143 offset:55296
	ds_read_b128 v[210:213], v143 offset:56320
	global_load_lds_dwordx4 v132, s[94:95]
	s_mov_b32 m0, s54
	s_nop 0
	global_load_lds_dwordx4 v130, s[94:95]
	s_barrier
	s_waitcnt lgkmcnt(0)
	v_mfma_f32_16x16x32_bf16 v[60:63], v[144:147], v[160:163], v[60:63]
	v_mfma_f32_16x16x32_bf16 v[56:59], v[152:155], v[160:163], v[56:59]
	v_mfma_f32_16x16x32_bf16 v[52:55], v[144:147], v[168:171], v[52:55]
	v_mfma_f32_16x16x32_bf16 v[44:47], v[152:155], v[168:171], v[44:47]
	v_mfma_f32_16x16x32_bf16 v[36:39], v[144:147], v[198:201], v[36:39]
	v_mfma_f32_16x16x32_bf16 v[28:31], v[152:155], v[198:201], v[28:31]
	v_mfma_f32_16x16x32_bf16 v[20:23], v[144:147], v[206:209], v[20:23]
	v_mfma_f32_16x16x32_bf16 v[12:15], v[152:155], v[206:209], v[12:15]
	v_mfma_f32_16x16x32_bf16 v[60:63], v[148:151], v[164:167], v[60:63]
	v_mfma_f32_16x16x32_bf16 v[56:59], v[156:159], v[164:167], v[56:59]
	v_mfma_f32_16x16x32_bf16 v[52:55], v[148:151], v[172:175], v[52:55]
	v_mfma_f32_16x16x32_bf16 v[44:47], v[156:159], v[172:175], v[44:47]
	v_mfma_f32_16x16x32_bf16 v[36:39], v[148:151], v[202:205], v[36:39]
	v_mfma_f32_16x16x32_bf16 v[28:31], v[156:159], v[202:205], v[28:31]
	v_mfma_f32_16x16x32_bf16 v[20:23], v[148:151], v[210:213], v[20:23]
	v_mfma_f32_16x16x32_bf16 v[12:15], v[156:159], v[210:213], v[12:15]
	s_barrier
	s_add_u32 s20, s28, 0x40080
	s_addc_u32 s21, s29, 0
	s_add_i32 s28, s48, s6
	s_mov_b32 m0, s28
	s_nop 0
	global_load_lds_dwordx4 v176, s[20:21]
	s_add_i32 m0, s28, 0x2000
	s_nop 0
	global_load_lds_dwordx4 v128, s[20:21]
	s_waitcnt vmcnt(6)
	s_barrier
	v_mfma_f32_16x16x32_bf16 v[48:51], v[214:217], v[160:163], v[48:51]
	v_mfma_f32_16x16x32_bf16 v[40:43], v[236:239], v[160:163], v[40:43]
	v_mfma_f32_16x16x32_bf16 v[32:35], v[214:217], v[168:171], v[32:35]
	v_mfma_f32_16x16x32_bf16 v[24:27], v[236:239], v[168:171], v[24:27]
	v_mfma_f32_16x16x32_bf16 v[16:19], v[214:217], v[198:201], v[16:19]
	v_mfma_f32_16x16x32_bf16 v[8:11], v[236:239], v[198:201], v[8:11]
	v_mfma_f32_16x16x32_bf16 v[4:7], v[214:217], v[206:209], v[4:7]
	v_mfma_f32_16x16x32_bf16 v[0:3], v[236:239], v[206:209], v[0:3]
	v_mfma_f32_16x16x32_bf16 v[48:51], v[232:235], v[164:167], v[48:51]
	v_mfma_f32_16x16x32_bf16 v[40:43], v[240:243], v[164:167], v[40:43]
	v_mfma_f32_16x16x32_bf16 v[32:35], v[232:235], v[172:175], v[32:35]
	v_mfma_f32_16x16x32_bf16 v[24:27], v[240:243], v[172:175], v[24:27]
	v_mfma_f32_16x16x32_bf16 v[16:19], v[232:235], v[202:205], v[16:19]
	v_mfma_f32_16x16x32_bf16 v[8:11], v[240:243], v[202:205], v[8:11]
	v_mfma_f32_16x16x32_bf16 v[4:7], v[232:235], v[210:213], v[4:7]
	v_mfma_f32_16x16x32_bf16 v[0:3], v[240:243], v[210:213], v[0:3]
	s_add_i32 vcc_lo, vcc_lo, 2
	s_add_u32 s46, s46, 0x100
	s_addc_u32 s47, s47, 0
	s_add_u32 s58, s58, 0x100
	s_addc_u32 s59, s59, 0
	s_cmp_gt_u32 vcc_lo, 13
	s_barrier
	s_cbranch_scc0 .LBB0_292
	v_lshl_add_u32 v144, s57, 8, v140
	v_lshl_or_b32 v138, s2, 8, v142
	v_ashrrev_i32_e32 v145, 31, v144
	v_readlane_b32 s20, v254, 43
	v_ashrrev_i32_e32 v139, 31, v138
	v_lshlrev_b64 v[146:147], 16, v[144:145]
	v_readlane_b32 s21, v254, 44
	v_lshlrev_b64 v[148:149], 1, v[138:139]
	v_cvt_pk_bf16_f32 v124, v124, v125
	v_cvt_pk_bf16_f32 v125, v126, v127
	v_cvt_pk_bf16_f32 v126, v120, v121
	v_cvt_pk_bf16_f32 v127, v122, v123
	s_nop 0
	v_lshl_add_u64 v[146:147], s[20:21], 0, v[146:147]
	v_lshl_add_u64 v[138:139], v[146:147], 0, v[148:149]
	global_store_dwordx4 v[138:139], v[124:127], off
	v_cvt_pk_bf16_f32 v112, v112, v113
	v_cvt_pk_bf16_f32 v113, v114, v115
	v_cvt_pk_bf16_f32 v114, v104, v105
	v_or_b32_e32 v104, 16, v144
	v_ashrrev_i32_e32 v105, 31, v104
	v_lshlrev_b64 v[104:105], 16, v[104:105]
	v_lshl_add_u64 v[104:105], s[20:21], 0, v[104:105]
	v_cvt_pk_bf16_f32 v115, v106, v107
	global_store_dwordx4 v[138:139], v[112:115], off offset:256
	s_mov_b32 s1, 0x900000
	s_mov_b32 s2, s0
	v_lshl_add_u64 v[112:113], v[104:105], 0, v[148:149]
	v_cvt_pk_bf16_f32 v104, v116, v117
	v_cvt_pk_bf16_f32 v105, v118, v119
	v_cvt_pk_bf16_f32 v106, v108, v109
	v_cvt_pk_bf16_f32 v107, v110, v111
	global_store_dwordx4 v[112:113], v[104:107], off
	v_cvt_pk_bf16_f32 v96, v96, v97
	v_cvt_pk_bf16_f32 v97, v98, v99
	v_cvt_pk_bf16_f32 v98, v88, v89
	v_or_b32_e32 v88, 32, v144
	v_ashrrev_i32_e32 v89, 31, v88
	v_lshlrev_b64 v[88:89], 16, v[88:89]
	v_lshl_add_u64 v[88:89], s[20:21], 0, v[88:89]
	v_cvt_pk_bf16_f32 v99, v90, v91
	global_store_dwordx4 v[112:113], v[96:99], off offset:256
	s_mov_b32 s57, s40
	s_mov_b64 s[28:29], s[44:45]
	v_lshl_add_u64 v[96:97], v[88:89], 0, v[148:149]
	v_cvt_pk_bf16_f32 v88, v100, v101
	v_cvt_pk_bf16_f32 v89, v102, v103
	v_cvt_pk_bf16_f32 v90, v92, v93
	v_cvt_pk_bf16_f32 v91, v94, v95
	global_store_dwordx4 v[96:97], v[88:91], off
	v_cvt_pk_bf16_f32 v84, v84, v85
	v_cvt_pk_bf16_f32 v85, v86, v87
	v_cvt_pk_bf16_f32 v86, v76, v77
	v_or_b32_e32 v76, 48, v144
	v_ashrrev_i32_e32 v77, 31, v76
	v_lshlrev_b64 v[76:77], 16, v[76:77]
	v_lshl_add_u64 v[76:77], s[20:21], 0, v[76:77]
	v_cvt_pk_bf16_f32 v87, v78, v79
	global_store_dwordx4 v[96:97], v[84:87], off offset:256
	s_mov_b64 s[20:21], 0x800000
	s_mov_b64 s[46:47], s[42:43]
	v_lshl_add_u64 v[84:85], v[76:77], 0, v[148:149]
	v_cvt_pk_bf16_f32 v76, v80, v81
	v_cvt_pk_bf16_f32 v77, v82, v83
	v_cvt_pk_bf16_f32 v78, v72, v73
	v_cvt_pk_bf16_f32 v79, v74, v75
	global_store_dwordx4 v[84:85], v[76:79], off
	v_cvt_pk_bf16_f32 v68, v68, v69
	v_cvt_pk_bf16_f32 v69, v70, v71
	v_cvt_pk_bf16_f32 v70, v64, v65
	v_cvt_pk_bf16_f32 v71, v66, v67
	global_store_dwordx4 v[84:85], v[68:71], off offset:256
	v_cvt_pk_bf16_f32 v60, v60, v61
	v_cvt_pk_bf16_f32 v61, v62, v63
	v_cvt_pk_bf16_f32 v62, v56, v57
	v_add_co_u32_e32 v56, vcc, s23, v138
	v_lshl_add_u64 v[64:65], v[138:139], 0, s[20:21]
	s_nop 0
	v_addc_co_u32_e32 v57, vcc, 0, v139, vcc
	v_cvt_pk_bf16_f32 v63, v58, v59
	global_store_dwordx4 v[56:57], v[60:63], off
	v_cvt_pk_bf16_f32 v48, v48, v49
	v_cvt_pk_bf16_f32 v49, v50, v51
	v_cvt_pk_bf16_f32 v50, v40, v41
	v_cvt_pk_bf16_f32 v51, v42, v43
	global_store_dwordx4 v[64:65], v[48:51], off offset:256
	s_mov_b64 s[20:21], 0x900000
	v_cvt_pk_bf16_f32 v40, v52, v53
	v_cvt_pk_bf16_f32 v41, v54, v55
	v_cvt_pk_bf16_f32 v42, v44, v45
	v_add_co_u32_e32 v44, vcc, s1, v138
	v_lshl_add_u64 v[48:49], v[138:139], 0, s[20:21]
	s_nop 0
	v_addc_co_u32_e32 v45, vcc, 0, v139, vcc
	s_mov_b32 s1, 0xa00000
	v_cvt_pk_bf16_f32 v43, v46, v47
	global_store_dwordx4 v[44:45], v[40:43], off
	v_cvt_pk_bf16_f32 v32, v32, v33
	v_cvt_pk_bf16_f32 v33, v34, v35
	v_cvt_pk_bf16_f32 v34, v24, v25
	v_cvt_pk_bf16_f32 v35, v26, v27
	global_store_dwordx4 v[48:49], v[32:35], off offset:256
	s_mov_b64 s[20:21], 0xa00000
	v_cvt_pk_bf16_f32 v24, v36, v37
	v_cvt_pk_bf16_f32 v25, v38, v39
	v_cvt_pk_bf16_f32 v26, v28, v29
	v_add_co_u32_e32 v28, vcc, s1, v138
	v_lshl_add_u64 v[32:33], v[138:139], 0, s[20:21]
	s_nop 0
	v_addc_co_u32_e32 v29, vcc, 0, v139, vcc
	s_mov_b32 s1, 0xb00000
	v_cvt_pk_bf16_f32 v27, v30, v31
	global_store_dwordx4 v[28:29], v[24:27], off
	v_cvt_pk_bf16_f32 v16, v16, v17
	v_cvt_pk_bf16_f32 v17, v18, v19
	v_cvt_pk_bf16_f32 v18, v8, v9
	v_cvt_pk_bf16_f32 v19, v10, v11
	global_store_dwordx4 v[32:33], v[16:19], off offset:256
	v_cvt_pk_bf16_f32 v8, v20, v21
	v_cvt_pk_bf16_f32 v9, v22, v23
	v_cvt_pk_bf16_f32 v10, v12, v13
	v_add_co_u32_e32 v12, vcc, s1, v138
	s_mov_b64 s[20:21], 0xb00000
	s_nop 0
	v_addc_co_u32_e32 v13, vcc, 0, v139, vcc
	v_lshl_add_u64 v[16:17], v[138:139], 0, s[20:21]
	s_and_b64 vcc, exec, s[38:39]
	v_cvt_pk_bf16_f32 v11, v14, v15
	global_store_dwordx4 v[12:13], v[8:11], off
	v_cvt_pk_bf16_f32 v4, v4, v5
	v_cvt_pk_bf16_f32 v5, v6, v7
	v_cvt_pk_bf16_f32 v6, v0, v1
	v_cvt_pk_bf16_f32 v7, v2, v3
	global_store_dwordx4 v[16:17], v[4:7], off offset:256
	s_cbranch_vccz .LBB0_285
	s_waitcnt vmcnt(0)
	v_readlane_b32 s54, v253, 37
	s_cmpk_gt_u32 s3, 0xff
	v_readlane_b32 s55, v253, 38
	s_cbranch_scc1 .LBB0_296
	s_barrier
